# MLA: one s_barrier per two 64-key slots (K tiles as a ring of 4, odd slots stage tiles t+2,t+3 into the slots last read in the previous slot pair)
# speedup vs baseline: 1.0293x; 1.0011x over previous
.LBB0_1885:
	s_or_b64 exec, exec, s[0:1]
	v_readlane_b32 s0, v250, 2
	v_readlane_b32 s1, v250, 3
	v_readlane_b32 s86, v250, 1
	s_andn2_b64 vcc, exec, s[0:1]
	s_waitcnt vmcnt(0) lgkmcnt(0)
	s_barrier
	s_cbranch_vccnz .LBB0_1920
	v_and_b32_e32 v234, 31, v0
	v_bfe_u32 v235, v0, 5, 1
	v_mul_u32_u24_e32 v220, 0xd0, v234
	v_lshl_add_u32 v220, v235, 4, v220
	v_mul_u32_u24_e32 v221, 0x90, v234
	v_lshl_add_u32 v221, v235, 4, v221
	v_add_u32_e32 v221, 0xd000, v221
	v_lshl_or_b32 v1, s87, 5, v234
	v_mul_u32_u24_e32 v237, 0xc0, v1
	v_lshl_add_u32 v237, v235, 4, v237
	v_lshlrev_b32_e32 v236, 10, v1
	v_lshl_add_u32 v236, v235, 3, v236
	v_lshlrev_b32_e32 v226, 4, v0
	v_add_u32_e32 v227, 0x2000, v226
	v_add_u32_e32 v228, 0x4000, v226
	v_lshrrev_b32_e32 v234, 3, v0
	v_and_b32_e32 v235, 7, v0
	v_mul_u32_u24_e32 v229, 0x2200, v234
	v_lshl_add_u32 v229, v235, 4, v229
	v_mul_u32_u24_e32 v225, 0x90, v234
	v_lshrrev_b32_e32 v1, 1, v235
	v_lshl_add_u32 v225, v1, 5, v225
	v_and_b32_e32 v1, 1, v235
	v_lshl_add_u32 v225, v1, 3, v225
	v_add_u32_e32 v225, 0xd000, v225
	s_mov_b32 s17, 0xaaab
	s_movk_i32 s18, 0xd0
	v_mov_b32_e32 v234, v0
	v_mul_lo_u32 v235, v234, s17
	v_lshrrev_b32_e32 v235, 19, v235
	v_mul_u32_u24_e32 v1, 12, v235
	v_sub_u32_e32 v234, v234, v1
	v_lshrrev_b32_e32 v1, 6, v235
	v_and_b32_e32 v235, 63, v235
	v_mul_u32_u24_e32 v1, 0x3400, v1
	v_mad_u32_u24 v1, v235, s18, v1
	v_lshl_add_u32 v222, v234, 4, v1
	v_cmp_gt_u32_e32 vcc, 0x3400, v1
	v_mov_b32_e32 v196, 0xffffcc00
	v_mov_b32_e32 v197, 0x9c00
	v_cndmask_b32_e32 v196, v196, v197, vcc
	v_add_u32_e32 v238, v222, v196
	v_add_u32_e32 v234, 512, v0
	v_mul_lo_u32 v235, v234, s17
	v_lshrrev_b32_e32 v235, 19, v235
	v_mul_u32_u24_e32 v1, 12, v235
	v_sub_u32_e32 v234, v234, v1
	v_lshrrev_b32_e32 v1, 6, v235
	v_and_b32_e32 v235, 63, v235
	v_mul_u32_u24_e32 v1, 0x3400, v1
	v_mad_u32_u24 v1, v235, s18, v1
	v_lshl_add_u32 v223, v234, 4, v1
	v_cmp_gt_u32_e32 vcc, 0x3400, v1
	v_mov_b32_e32 v196, 0xffffcc00
	v_mov_b32_e32 v197, 0x9c00
	v_cndmask_b32_e32 v196, v196, v197, vcc
	v_add_u32_e32 v239, v223, v196
	v_add_u32_e32 v234, 1024, v0
	v_mul_lo_u32 v235, v234, s17
	v_lshrrev_b32_e32 v235, 19, v235
	v_mul_u32_u24_e32 v1, 12, v235
	v_sub_u32_e32 v234, v234, v1
	v_lshrrev_b32_e32 v1, 6, v235
	v_and_b32_e32 v235, 63, v235
	v_mul_u32_u24_e32 v1, 0x3400, v1
	v_mad_u32_u24 v1, v235, s18, v1
	v_lshl_add_u32 v224, v234, 4, v1
	v_cmp_gt_u32_e32 vcc, 0x3400, v1
	v_mov_b32_e32 v196, 0xffffcc00
	v_mov_b32_e32 v197, 0x9c00
	v_cndmask_b32_e32 v196, v196, v197, vcc
	v_add_u32_e32 v240, v224, v196
	v_mov_b32_e32 v234, 0
	v_mov_b32_e32 v235, 0x186a0
	ds_write_b32 v235, v234
.Lmla_restart:
	s_lshr_b32 s17, s2, 4
	s_and_b32 s18, s2, 15
	s_mul_i32 s19, s17, 0xcc000
	s_add_u32 s4, s78, s19
	s_addc_u32 s5, s79, 0
	s_mul_i32 s19, s17, 0x88000
	s_add_u32 s19, s19, 0x1a00000
	s_add_u32 s10, s78, s19
	s_addc_u32 s11, s79, 0
	s_lshl_b32 s19, s17, 12
	s_lshl_b32 s20, s18, 8
	s_add_u32 s19, s19, s20
	s_mul_i32 s19, s19, 0xc0
	s_add_u32 s19, s19, 0x1400000
	s_add_u32 s12, s80, s19
	s_addc_u32 s13, s81, 0
	s_lshr_b32 s19, s17, 3
	s_lshl_b32 s19, s19, 12
	s_add_u32 s19, s19, s20
	s_lshl_b32 s19, s19, 10
	s_and_b32 s21, s17, 7
	s_lshl_b32 s21, s21, 7
	s_add_u32 s19, s19, s21
	s_add_u32 s19, s19, 0x7900000
	s_add_u32 s14, s80, s19
	s_addc_u32 s15, s81, 0
	global_load_dwordx4 v[98:101], v237, s[12:13] offset:0
	global_load_dwordx4 v[102:105], v237, s[12:13] offset:32
	global_load_dwordx4 v[106:109], v237, s[12:13] offset:64
	global_load_dwordx4 v[110:113], v237, s[12:13] offset:96
	global_load_dwordx4 v[114:117], v237, s[12:13] offset:128
	global_load_dwordx4 v[118:121], v237, s[12:13] offset:160
	global_load_dwordx4 v[34:37], v226, s[4:5]
	global_load_dwordx4 v[38:41], v227, s[4:5]
	global_load_dwordx4 v[42:45], v228, s[4:5]
	global_load_dwordx4 v[46:49], v229, s[10:11]
	s_add_u32 s4, s4, 0x6000
	s_addc_u32 s5, s5, 0
	global_load_dwordx4 v[50:53], v226, s[4:5]
	global_load_dwordx4 v[54:57], v227, s[4:5]
	global_load_dwordx4 v[58:61], v228, s[4:5]
	global_load_dwordx4 v[62:65], v229, s[10:11] offset:128
	global_load_dwordx4 v[216:219], v229, s[10:11] offset:256
	s_add_u32 s4, s4, 0x3000
	s_addc_u32 s5, s5, 0
	s_add_u32 s10, s10, 0x180
	s_addc_u32 s11, s11, 0
	v_mov_b32_e32 v2, 0
	v_mov_b32_e32 v3, 0
	v_mov_b32_e32 v4, 0
	v_mov_b32_e32 v5, 0
	v_mov_b32_e32 v6, 0
	v_mov_b32_e32 v7, 0
	v_mov_b32_e32 v8, 0
	v_mov_b32_e32 v9, 0
	v_mov_b32_e32 v10, 0
	v_mov_b32_e32 v11, 0
	v_mov_b32_e32 v12, 0
	v_mov_b32_e32 v13, 0
	v_mov_b32_e32 v14, 0
	v_mov_b32_e32 v15, 0
	v_mov_b32_e32 v16, 0
	v_mov_b32_e32 v17, 0
	v_mov_b32_e32 v18, 0
	v_mov_b32_e32 v19, 0
	v_mov_b32_e32 v20, 0
	v_mov_b32_e32 v21, 0
	v_mov_b32_e32 v22, 0
	v_mov_b32_e32 v23, 0
	v_mov_b32_e32 v24, 0
	v_mov_b32_e32 v25, 0
	v_mov_b32_e32 v26, 0
	v_mov_b32_e32 v27, 0
	v_mov_b32_e32 v28, 0
	v_mov_b32_e32 v29, 0
	v_mov_b32_e32 v30, 0
	v_mov_b32_e32 v31, 0
	v_mov_b32_e32 v32, 0
	v_mov_b32_e32 v33, 0
	v_mov_b32_e32 v122, 0
	v_mov_b32_e32 v123, 0
	v_mov_b32_e32 v124, 0
	v_mov_b32_e32 v125, 0
	v_mov_b32_e32 v126, 0
	v_mov_b32_e32 v127, 0
	v_mov_b32_e32 v128, 0
	v_mov_b32_e32 v129, 0
	v_mov_b32_e32 v130, 0
	v_mov_b32_e32 v131, 0
	v_mov_b32_e32 v132, 0
	v_mov_b32_e32 v133, 0
	v_mov_b32_e32 v134, 0
	v_mov_b32_e32 v135, 0
	v_mov_b32_e32 v136, 0
	v_mov_b32_e32 v137, 0
	v_mov_b32_e32 v230, 0
	v_mov_b32_e32 v231, 0
	v_mov_b32_e32 v232, 0
	s_waitcnt vmcnt(5)
	ds_write_b128 v222, v[34:37]
	ds_write_b128 v223, v[38:41]
	ds_write_b128 v224, v[42:45]
	ds_write_b64 v225, v[46:47]
	ds_write_b64 v225, v[48:49] offset:16
	s_waitcnt vmcnt(1)
	ds_write_b128 v222, v[50:53] offset:26624
	ds_write_b128 v223, v[54:57] offset:26624
	ds_write_b128 v224, v[58:61] offset:26624
	ds_write_b64 v225, v[62:63] offset:9216
	ds_write_b64 v225, v[64:65] offset:9232
	s_waitcnt lgkmcnt(0)
	s_barrier
.Lmla_body:
	ds_read_b128 v[138:141], v220 offset:0
	ds_read_b128 v[142:145], v220 offset:6656
	ds_read_b128 v[146:149], v220 offset:32
	ds_read_b128 v[150:153], v220 offset:6688
	ds_read_b128 v[154:157], v220 offset:64
	ds_read_b128 v[158:161], v220 offset:6720
	ds_read_b128 v[66:69], v220 offset:96
	ds_read_b128 v[70:73], v220 offset:6752
	ds_read_b128 v[74:77], v220 offset:128
	ds_read_b128 v[78:81], v220 offset:6784
	ds_read_b128 v[82:85], v220 offset:160
	ds_read_b128 v[86:89], v220 offset:6816
	s_waitcnt lgkmcnt(11)
	v_mfma_f32_32x32x16_bf16 v[34:49], v[138:141], v[98:101], v[122:137]
	s_waitcnt lgkmcnt(10)
	v_mfma_f32_32x32x16_bf16 v[50:65], v[142:145], v[98:101], v[122:137]
	s_waitcnt lgkmcnt(9)
	v_mfma_f32_32x32x16_bf16 v[34:49], v[146:149], v[102:105], v[34:49]
	s_waitcnt lgkmcnt(8)
	v_mfma_f32_32x32x16_bf16 v[50:65], v[150:153], v[102:105], v[50:65]
	s_waitcnt lgkmcnt(7)
	v_mfma_f32_32x32x16_bf16 v[34:49], v[154:157], v[106:109], v[34:49]
	s_waitcnt lgkmcnt(6)
	v_mfma_f32_32x32x16_bf16 v[50:65], v[158:161], v[106:109], v[50:65]
	s_waitcnt lgkmcnt(5)
	v_mfma_f32_32x32x16_bf16 v[34:49], v[66:69], v[110:113], v[34:49]
	s_waitcnt lgkmcnt(4)
	v_mfma_f32_32x32x16_bf16 v[50:65], v[70:73], v[110:113], v[50:65]
	s_waitcnt lgkmcnt(3)
	v_mfma_f32_32x32x16_bf16 v[34:49], v[74:77], v[114:117], v[34:49]
	s_waitcnt lgkmcnt(2)
	v_mfma_f32_32x32x16_bf16 v[50:65], v[78:81], v[114:117], v[50:65]
	s_waitcnt lgkmcnt(1)
	v_mfma_f32_32x32x16_bf16 v[34:49], v[82:85], v[118:121], v[34:49]
	s_waitcnt lgkmcnt(0)
	v_mfma_f32_32x32x16_bf16 v[50:65], v[86:89], v[118:121], v[50:65]
	s_barrier
	s_nop 15
	v_max3_f32 v234, v34, v35, v36
	v_max3_f32 v235, v50, v51, v52
	v_max3_f32 v234, v234, v37, v38
	v_max3_f32 v235, v235, v53, v54
	v_max3_f32 v234, v234, v39, v40
	v_max3_f32 v235, v235, v55, v56
	v_max3_f32 v234, v234, v41, v42
	v_max3_f32 v235, v235, v57, v58
	v_max3_f32 v234, v234, v43, v44
	v_max3_f32 v235, v235, v59, v60
	v_max3_f32 v234, v234, v45, v46
	v_max3_f32 v235, v235, v61, v62
	v_max3_f32 v234, v234, v47, v48
	v_max3_f32 v235, v235, v63, v64
	v_max3_f32 v234, v234, v49, v65
	v_max_f32_e32 v234, v234, v235
	v_mov_b32_e32 v235, v234
	s_nop 1
	v_permlane32_swap_b32_e32 v234, v235
	v_max_f32_e32 v233, v234, v235
	s_nop 15
	v_add_f32_e32 v230, v230, v233
	v_sub_f32_e32 v34, v34, v233
	v_sub_f32_e32 v35, v35, v233
	v_sub_f32_e32 v36, v36, v233
	v_sub_f32_e32 v37, v37, v233
	v_sub_f32_e32 v38, v38, v233
	v_sub_f32_e32 v39, v39, v233
	v_sub_f32_e32 v40, v40, v233
	v_sub_f32_e32 v41, v41, v233
	v_sub_f32_e32 v42, v42, v233
	v_sub_f32_e32 v43, v43, v233
	v_sub_f32_e32 v44, v44, v233
	v_sub_f32_e32 v45, v45, v233
	v_sub_f32_e32 v46, v46, v233
	v_sub_f32_e32 v47, v47, v233
	v_sub_f32_e32 v48, v48, v233
	v_sub_f32_e32 v49, v49, v233
	v_sub_f32_e32 v50, v50, v233
	v_sub_f32_e32 v51, v51, v233
	v_sub_f32_e32 v52, v52, v233
	v_sub_f32_e32 v53, v53, v233
	v_sub_f32_e32 v54, v54, v233
	v_sub_f32_e32 v55, v55, v233
	v_sub_f32_e32 v56, v56, v233
	v_sub_f32_e32 v57, v57, v233
	v_sub_f32_e32 v58, v58, v233
	v_sub_f32_e32 v59, v59, v233
	v_sub_f32_e32 v60, v60, v233
	v_sub_f32_e32 v61, v61, v233
	v_sub_f32_e32 v62, v62, v233
	v_sub_f32_e32 v63, v63, v233
	v_sub_f32_e32 v64, v64, v233
	v_sub_f32_e32 v65, v65, v233
	v_sub_f32_e32 v122, 0, v230
	v_mov_b32_e32 v123, v122
	v_mov_b32_e32 v124, v122
	v_mov_b32_e32 v125, v122
	v_mov_b32_e32 v126, v122
	v_mov_b32_e32 v127, v122
	v_mov_b32_e32 v128, v122
	v_mov_b32_e32 v129, v122
	v_mov_b32_e32 v130, v122
	v_mov_b32_e32 v131, v122
	v_mov_b32_e32 v132, v122
	v_mov_b32_e32 v133, v122
	v_mov_b32_e32 v134, v122
	v_mov_b32_e32 v135, v122
	v_mov_b32_e32 v136, v122
	v_mov_b32_e32 v137, v122
	s_movk_i32 s16, 16
.Lmla_loop:
	ds_read_b128 v[138:141], v220 offset:13312
	ds_read_b128 v[142:145], v220 offset:19968
	ds_read_b128 v[146:149], v220 offset:13344
	ds_read_b128 v[150:153], v220 offset:20000
	ds_read_b128 v[154:157], v220 offset:13376
	ds_read_b128 v[158:161], v220 offset:20032
	v_exp_f32_e32 v34, v34
	v_exp_f32_e32 v35, v35
	v_exp_f32_e32 v36, v36
	s_waitcnt lgkmcnt(4)
	v_mfma_f32_32x32x16_bf16 v[66:81], v[138:141], v[98:101], v[122:137]
	ds_read_b128 v[138:141], v220 offset:13408
	v_exp_f32_e32 v37, v37
	v_add_f32_e32 v231, v231, v34
	v_add_f32_e32 v232, v232, v35
	v_exp_f32_e32 v38, v38
	v_mfma_f32_32x32x16_bf16 v[82:97], v[142:145], v[98:101], v[122:137]
	ds_read_b128 v[142:145], v220 offset:20064
	v_exp_f32_e32 v39, v39
	v_add_f32_e32 v231, v231, v36
	v_add_f32_e32 v232, v232, v37
	s_waitcnt lgkmcnt(4)
	v_mfma_f32_32x32x16_bf16 v[66:81], v[146:149], v[102:105], v[66:81]
	ds_read_b128 v[146:149], v220 offset:13440
	global_load_dwordx4 v[200:203], v226, s[4:5]
	global_load_dwordx4 v[204:207], v227, s[4:5]
	global_load_dwordx4 v[208:211], v228, s[4:5]
	s_add_u32 s4, s4, 0x6000
	s_addc_u32 s5, s5, 0
	global_load_dwordx4 v[212:215], v229, s[10:11]
	s_add_u32 s10, s10, 0x80
	s_addc_u32 s11, s11, 0
	v_exp_f32_e32 v40, v40
	v_exp_f32_e32 v41, v41
	v_add_f32_e32 v231, v231, v38
	v_add_f32_e32 v232, v232, v39
	v_mfma_f32_32x32x16_bf16 v[82:97], v[150:153], v[102:105], v[82:97]
	ds_read_b128 v[150:153], v220 offset:20096
	v_add_f32_e32 v231, v231, v40
	v_add_f32_e32 v232, v232, v41
	v_cvt_pk_bf16_f32 v34, v34, v35
	v_cvt_pk_bf16_f32 v35, v36, v37
	v_cvt_pk_bf16_f32 v36, v38, v39
	s_waitcnt lgkmcnt(4)
	v_mfma_f32_32x32x16_bf16 v[66:81], v[154:157], v[106:109], v[66:81]
	ds_read_b128 v[154:157], v220 offset:13472
	v_cvt_pk_bf16_f32 v37, v40, v41
	v_exp_f32_e32 v42, v42
	v_exp_f32_e32 v43, v43
	v_mfma_f32_32x32x16_bf16 v[82:97], v[158:161], v[106:109], v[82:97]
	ds_read_b128 v[158:161], v220 offset:20128
	v_exp_f32_e32 v44, v44
	v_exp_f32_e32 v45, v45
	v_add_f32_e32 v231, v231, v42
	v_add_f32_e32 v232, v232, v43
	s_waitcnt lgkmcnt(4)
	v_mfma_f32_32x32x16_bf16 v[66:81], v[138:141], v[110:113], v[66:81]
	ds_read_b128 v[162:165], v221 offset:0
	v_exp_f32_e32 v46, v46
	v_exp_f32_e32 v47, v47
	v_add_f32_e32 v231, v231, v44
	v_mfma_f32_32x32x16_bf16 v[82:97], v[142:145], v[110:113], v[82:97]
	ds_read_b128 v[166:169], v221 offset:4608
	v_add_f32_e32 v232, v232, v45
	v_exp_f32_e32 v48, v48
	v_exp_f32_e32 v49, v49
	s_waitcnt lgkmcnt(4)
	v_mfma_f32_32x32x16_bf16 v[66:81], v[146:149], v[114:117], v[66:81]
	ds_read_b128 v[170:173], v221 offset:32
	v_add_f32_e32 v231, v231, v46
	v_add_f32_e32 v232, v232, v47
	v_add_f32_e32 v231, v231, v48
	v_add_f32_e32 v232, v232, v49
	v_cvt_pk_bf16_f32 v42, v42, v43
	v_cvt_pk_bf16_f32 v43, v44, v45
	v_mfma_f32_32x32x16_bf16 v[82:97], v[150:153], v[114:117], v[82:97]
	ds_read_b128 v[174:177], v221 offset:4640
	v_cvt_pk_bf16_f32 v44, v46, v47
	v_cvt_pk_bf16_f32 v45, v48, v49
	v_exp_f32_e32 v50, v50
	v_exp_f32_e32 v51, v51
	s_waitcnt lgkmcnt(4)
	v_mfma_f32_32x32x16_bf16 v[66:81], v[154:157], v[118:121], v[66:81]
	ds_read_b128 v[180:183], v221 offset:64
	v_exp_f32_e32 v52, v52
	v_exp_f32_e32 v53, v53
	v_mfma_f32_32x32x16_bf16 v[82:97], v[158:161], v[118:121], v[82:97]
	ds_read_b128 v[184:187], v221 offset:4672
	v_add_f32_e32 v231, v231, v50
	v_add_f32_e32 v232, v232, v51
	v_exp_f32_e32 v54, v54
	v_exp_f32_e32 v55, v55
	s_waitcnt lgkmcnt(4)
	v_mfma_f32_32x32x16_bf16 v[2:17], v[162:165], v[34:37], v[2:17]
	ds_read_b128 v[188:191], v221 offset:96
	v_add_f32_e32 v231, v231, v52
	v_add_f32_e32 v232, v232, v53
	v_exp_f32_e32 v56, v56
	v_exp_f32_e32 v57, v57
	v_mfma_f32_32x32x16_bf16 v[18:33], v[166:169], v[34:37], v[18:33]
	ds_read_b128 v[192:195], v221 offset:4704
	v_add_f32_e32 v231, v231, v54
	v_add_f32_e32 v232, v232, v55
	v_add_f32_e32 v231, v231, v56
	v_add_f32_e32 v232, v232, v57
	s_waitcnt lgkmcnt(4)
	v_mfma_f32_32x32x16_bf16 v[2:17], v[170:173], v[42:45], v[2:17]
	v_cvt_pk_bf16_f32 v50, v50, v51
	v_cvt_pk_bf16_f32 v51, v52, v53
	v_cvt_pk_bf16_f32 v52, v54, v55
	v_cvt_pk_bf16_f32 v53, v56, v57
	v_exp_f32_e32 v58, v58
	v_mfma_f32_32x32x16_bf16 v[18:33], v[174:177], v[42:45], v[18:33]
	s_waitcnt vmcnt(4)
	ds_write_b64 v225, v[216:217] offset:18432
	ds_write_b64 v225, v[218:219] offset:18448
	v_exp_f32_e32 v59, v59
	v_exp_f32_e32 v60, v60
	v_exp_f32_e32 v61, v61
	s_waitcnt lgkmcnt(4)
	v_mfma_f32_32x32x16_bf16 v[2:17], v[180:183], v[50:53], v[2:17]
	v_add_f32_e32 v231, v231, v58
	v_add_f32_e32 v232, v232, v59
	v_exp_f32_e32 v62, v62
	v_mfma_f32_32x32x16_bf16 v[18:33], v[184:187], v[50:53], v[18:33]
	v_exp_f32_e32 v63, v63
	v_add_f32_e32 v231, v231, v60
	v_add_f32_e32 v232, v232, v61
	v_exp_f32_e32 v64, v64
	v_exp_f32_e32 v65, v65
	v_add_f32_e32 v231, v231, v62
	v_add_f32_e32 v232, v232, v63
	v_add_f32_e32 v231, v231, v64
	v_add_f32_e32 v232, v232, v65
	v_cvt_pk_bf16_f32 v58, v58, v59
	v_cvt_pk_bf16_f32 v59, v60, v61
	v_cvt_pk_bf16_f32 v60, v62, v63
	v_cvt_pk_bf16_f32 v61, v64, v65
	s_waitcnt lgkmcnt(2)
	s_nop 0
	v_mfma_f32_32x32x16_bf16 v[2:17], v[188:191], v[58:61], v[2:17]
	v_mfma_f32_32x32x16_bf16 v[18:33], v[192:195], v[58:61], v[18:33]
	ds_read_b128 v[138:141], v220 offset:26624
	ds_read_b128 v[142:145], v220 offset:33280
	ds_read_b128 v[146:149], v220 offset:26656
	ds_read_b128 v[150:153], v220 offset:33312
	ds_read_b128 v[154:157], v220 offset:26688
	ds_read_b128 v[158:161], v220 offset:33344
	s_waitcnt lgkmcnt(6)
	v_exp_f32_e32 v66, v66
	v_exp_f32_e32 v67, v67
	v_exp_f32_e32 v68, v68
	s_waitcnt lgkmcnt(4)
	v_mfma_f32_32x32x16_bf16 v[34:49], v[138:141], v[98:101], v[122:137]
	ds_read_b128 v[138:141], v220 offset:26720
	v_exp_f32_e32 v69, v69
	v_add_f32_e32 v231, v231, v66
	v_add_f32_e32 v232, v232, v67
	v_exp_f32_e32 v70, v70
	v_mfma_f32_32x32x16_bf16 v[50:65], v[142:145], v[98:101], v[122:137]
	ds_read_b128 v[142:145], v220 offset:33376
	v_exp_f32_e32 v71, v71
	v_add_f32_e32 v231, v231, v68
	v_add_f32_e32 v232, v232, v69
	s_waitcnt lgkmcnt(4)
	v_mfma_f32_32x32x16_bf16 v[34:49], v[146:149], v[102:105], v[34:49]
	ds_read_b128 v[146:149], v220 offset:26752
	global_load_dwordx4 v[216:219], v229, s[10:11]
	s_add_u32 s10, s10, 0x80
	s_addc_u32 s11, s11, 0
	v_exp_f32_e32 v72, v72
	v_exp_f32_e32 v73, v73
	v_add_f32_e32 v231, v231, v70
	v_add_f32_e32 v232, v232, v71
	v_mfma_f32_32x32x16_bf16 v[50:65], v[150:153], v[102:105], v[50:65]
	ds_read_b128 v[150:153], v220 offset:33408
	v_add_f32_e32 v231, v231, v72
	v_add_f32_e32 v232, v232, v73
	v_cvt_pk_bf16_f32 v66, v66, v67
	v_cvt_pk_bf16_f32 v67, v68, v69
	v_cvt_pk_bf16_f32 v68, v70, v71
	s_waitcnt lgkmcnt(4)
	v_mfma_f32_32x32x16_bf16 v[34:49], v[154:157], v[106:109], v[34:49]
	ds_read_b128 v[154:157], v220 offset:26784
	v_cvt_pk_bf16_f32 v69, v72, v73
	v_exp_f32_e32 v74, v74
	v_exp_f32_e32 v75, v75
	v_mfma_f32_32x32x16_bf16 v[50:65], v[158:161], v[106:109], v[50:65]
	ds_read_b128 v[158:161], v220 offset:33440
	v_exp_f32_e32 v76, v76
	v_exp_f32_e32 v77, v77
	v_add_f32_e32 v231, v231, v74
	v_add_f32_e32 v232, v232, v75
	s_waitcnt lgkmcnt(4)
	v_mfma_f32_32x32x16_bf16 v[34:49], v[138:141], v[110:113], v[34:49]
	ds_read_b128 v[162:165], v221 offset:9216
	v_exp_f32_e32 v78, v78
	v_exp_f32_e32 v79, v79
	v_add_f32_e32 v231, v231, v76
	v_mfma_f32_32x32x16_bf16 v[50:65], v[142:145], v[110:113], v[50:65]
	ds_read_b128 v[166:169], v221 offset:13824
	v_add_f32_e32 v232, v232, v77
	v_exp_f32_e32 v80, v80
	v_exp_f32_e32 v81, v81
	s_waitcnt lgkmcnt(4)
	v_mfma_f32_32x32x16_bf16 v[34:49], v[146:149], v[114:117], v[34:49]
	ds_read_b128 v[170:173], v221 offset:9248
	v_add_f32_e32 v231, v231, v78
	v_add_f32_e32 v232, v232, v79
	v_add_f32_e32 v231, v231, v80
	v_add_f32_e32 v232, v232, v81
	v_cvt_pk_bf16_f32 v74, v74, v75
	v_cvt_pk_bf16_f32 v75, v76, v77
	v_mfma_f32_32x32x16_bf16 v[50:65], v[150:153], v[114:117], v[50:65]
	ds_read_b128 v[174:177], v221 offset:13856
	v_cvt_pk_bf16_f32 v76, v78, v79
	v_cvt_pk_bf16_f32 v77, v80, v81
	v_exp_f32_e32 v82, v82
	v_exp_f32_e32 v83, v83
	s_waitcnt lgkmcnt(4)
	v_mfma_f32_32x32x16_bf16 v[34:49], v[154:157], v[118:121], v[34:49]
	ds_read_b128 v[180:183], v221 offset:9280
	v_exp_f32_e32 v84, v84
	v_exp_f32_e32 v85, v85
	v_mfma_f32_32x32x16_bf16 v[50:65], v[158:161], v[118:121], v[50:65]
	ds_read_b128 v[184:187], v221 offset:13888
	v_add_f32_e32 v231, v231, v82
	v_add_f32_e32 v232, v232, v83
	v_exp_f32_e32 v86, v86
	v_exp_f32_e32 v87, v87
	s_waitcnt lgkmcnt(4)
	v_mfma_f32_32x32x16_bf16 v[2:17], v[162:165], v[66:69], v[2:17]
	ds_read_b128 v[188:191], v221 offset:9312
	v_add_f32_e32 v231, v231, v84
	v_add_f32_e32 v232, v232, v85
	v_exp_f32_e32 v88, v88
	v_exp_f32_e32 v89, v89
	v_mfma_f32_32x32x16_bf16 v[18:33], v[166:169], v[66:69], v[18:33]
	ds_read_b128 v[192:195], v221 offset:13920
	v_add_f32_e32 v231, v231, v86
	v_add_f32_e32 v232, v232, v87
	v_add_f32_e32 v231, v231, v88
	v_add_f32_e32 v232, v232, v89
	s_waitcnt lgkmcnt(4)
	v_mfma_f32_32x32x16_bf16 v[2:17], v[170:173], v[74:77], v[2:17]
	v_cvt_pk_bf16_f32 v82, v82, v83
	v_cvt_pk_bf16_f32 v83, v84, v85
	v_cvt_pk_bf16_f32 v84, v86, v87
	v_cvt_pk_bf16_f32 v85, v88, v89
	v_exp_f32_e32 v90, v90
	v_mfma_f32_32x32x16_bf16 v[18:33], v[174:177], v[74:77], v[18:33]
	s_waitcnt vmcnt(1)
	ds_write_b128 v238, v[200:203]
	ds_write_b128 v239, v[204:207]
	ds_write_b128 v240, v[208:211]
	ds_write_b64 v225, v[212:213] offset:27648
	ds_write_b64 v225, v[214:215] offset:27664
	v_exp_f32_e32 v91, v91
	v_exp_f32_e32 v92, v92
	v_exp_f32_e32 v93, v93
	s_waitcnt lgkmcnt(7)
	v_mfma_f32_32x32x16_bf16 v[2:17], v[180:183], v[82:85], v[2:17]
	v_add_f32_e32 v231, v231, v90
	v_add_f32_e32 v232, v232, v91
	v_exp_f32_e32 v94, v94
	v_mfma_f32_32x32x16_bf16 v[18:33], v[184:187], v[82:85], v[18:33]
	v_exp_f32_e32 v95, v95
	v_add_f32_e32 v231, v231, v92
	v_add_f32_e32 v232, v232, v93
	v_exp_f32_e32 v96, v96
	v_exp_f32_e32 v97, v97
	v_add_f32_e32 v231, v231, v94
	v_add_f32_e32 v232, v232, v95
	v_add_f32_e32 v231, v231, v96
	v_add_f32_e32 v232, v232, v97
	v_cvt_pk_bf16_f32 v90, v90, v91
	v_cvt_pk_bf16_f32 v91, v92, v93
	v_cvt_pk_bf16_f32 v92, v94, v95
	v_cvt_pk_bf16_f32 v93, v96, v97
	s_waitcnt lgkmcnt(5)
	s_nop 0
	v_mfma_f32_32x32x16_bf16 v[2:17], v[188:191], v[90:93], v[2:17]
	v_mfma_f32_32x32x16_bf16 v[18:33], v[192:195], v[90:93], v[18:33]
	s_waitcnt lgkmcnt(0)
	s_barrier
	ds_read_b128 v[138:141], v220 offset:39936
	ds_read_b128 v[142:145], v220 offset:46592
	ds_read_b128 v[146:149], v220 offset:39968
	ds_read_b128 v[150:153], v220 offset:46624
	ds_read_b128 v[154:157], v220 offset:40000
	ds_read_b128 v[158:161], v220 offset:46656
	v_exp_f32_e32 v34, v34
	v_exp_f32_e32 v35, v35
	v_exp_f32_e32 v36, v36
	s_waitcnt lgkmcnt(4)
	v_mfma_f32_32x32x16_bf16 v[66:81], v[138:141], v[98:101], v[122:137]
	ds_read_b128 v[138:141], v220 offset:40032
	v_exp_f32_e32 v37, v37
	v_add_f32_e32 v231, v231, v34
	v_add_f32_e32 v232, v232, v35
	v_exp_f32_e32 v38, v38
	v_mfma_f32_32x32x16_bf16 v[82:97], v[142:145], v[98:101], v[122:137]
	ds_read_b128 v[142:145], v220 offset:46688
	v_exp_f32_e32 v39, v39
	v_add_f32_e32 v231, v231, v36
	v_add_f32_e32 v232, v232, v37
	s_waitcnt lgkmcnt(4)
	v_mfma_f32_32x32x16_bf16 v[66:81], v[146:149], v[102:105], v[66:81]
	ds_read_b128 v[146:149], v220 offset:40064
	global_load_dwordx4 v[200:203], v226, s[4:5]
	global_load_dwordx4 v[204:207], v227, s[4:5]
	global_load_dwordx4 v[208:211], v228, s[4:5]
	s_add_u32 s4, s4, 0x6000
	s_addc_u32 s5, s5, 0
	global_load_dwordx4 v[212:215], v229, s[10:11]
	s_add_u32 s10, s10, 0x80
	s_addc_u32 s11, s11, 0
	v_exp_f32_e32 v40, v40
	v_exp_f32_e32 v41, v41
	v_add_f32_e32 v231, v231, v38
	v_add_f32_e32 v232, v232, v39
	v_mfma_f32_32x32x16_bf16 v[82:97], v[150:153], v[102:105], v[82:97]
	ds_read_b128 v[150:153], v220 offset:46720
	v_add_f32_e32 v231, v231, v40
	v_add_f32_e32 v232, v232, v41
	v_cvt_pk_bf16_f32 v34, v34, v35
	v_cvt_pk_bf16_f32 v35, v36, v37
	v_cvt_pk_bf16_f32 v36, v38, v39
	s_waitcnt lgkmcnt(4)
	v_mfma_f32_32x32x16_bf16 v[66:81], v[154:157], v[106:109], v[66:81]
	ds_read_b128 v[154:157], v220 offset:40096
	v_cvt_pk_bf16_f32 v37, v40, v41
	v_exp_f32_e32 v42, v42
	v_exp_f32_e32 v43, v43
	v_mfma_f32_32x32x16_bf16 v[82:97], v[158:161], v[106:109], v[82:97]
	ds_read_b128 v[158:161], v220 offset:46752
	v_exp_f32_e32 v44, v44
	v_exp_f32_e32 v45, v45
	v_add_f32_e32 v231, v231, v42
	v_add_f32_e32 v232, v232, v43
	s_waitcnt lgkmcnt(4)
	v_mfma_f32_32x32x16_bf16 v[66:81], v[138:141], v[110:113], v[66:81]
	ds_read_b128 v[162:165], v221 offset:18432
	v_exp_f32_e32 v46, v46
	v_exp_f32_e32 v47, v47
	v_add_f32_e32 v231, v231, v44
	v_mfma_f32_32x32x16_bf16 v[82:97], v[142:145], v[110:113], v[82:97]
	ds_read_b128 v[166:169], v221 offset:23040
	v_add_f32_e32 v232, v232, v45
	v_exp_f32_e32 v48, v48
	v_exp_f32_e32 v49, v49
	s_waitcnt lgkmcnt(4)
	v_mfma_f32_32x32x16_bf16 v[66:81], v[146:149], v[114:117], v[66:81]
	ds_read_b128 v[170:173], v221 offset:18464
	v_add_f32_e32 v231, v231, v46
	v_add_f32_e32 v232, v232, v47
	v_add_f32_e32 v231, v231, v48
	v_add_f32_e32 v232, v232, v49
	v_cvt_pk_bf16_f32 v42, v42, v43
	v_cvt_pk_bf16_f32 v43, v44, v45
	v_mfma_f32_32x32x16_bf16 v[82:97], v[150:153], v[114:117], v[82:97]
	ds_read_b128 v[174:177], v221 offset:23072
	v_cvt_pk_bf16_f32 v44, v46, v47
	v_cvt_pk_bf16_f32 v45, v48, v49
	v_exp_f32_e32 v50, v50
	v_exp_f32_e32 v51, v51
	s_waitcnt lgkmcnt(4)
	v_mfma_f32_32x32x16_bf16 v[66:81], v[154:157], v[118:121], v[66:81]
	ds_read_b128 v[180:183], v221 offset:18496
	v_exp_f32_e32 v52, v52
	v_exp_f32_e32 v53, v53
	v_mfma_f32_32x32x16_bf16 v[82:97], v[158:161], v[118:121], v[82:97]
	ds_read_b128 v[184:187], v221 offset:23104
	v_add_f32_e32 v231, v231, v50
	v_add_f32_e32 v232, v232, v51
	v_exp_f32_e32 v54, v54
	v_exp_f32_e32 v55, v55
	s_waitcnt lgkmcnt(4)
	v_mfma_f32_32x32x16_bf16 v[2:17], v[162:165], v[34:37], v[2:17]
	ds_read_b128 v[188:191], v221 offset:18528
	v_add_f32_e32 v231, v231, v52
	v_add_f32_e32 v232, v232, v53
	v_exp_f32_e32 v56, v56
	v_exp_f32_e32 v57, v57
	v_mfma_f32_32x32x16_bf16 v[18:33], v[166:169], v[34:37], v[18:33]
	ds_read_b128 v[192:195], v221 offset:23136
	v_add_f32_e32 v231, v231, v54
	v_add_f32_e32 v232, v232, v55
	v_add_f32_e32 v231, v231, v56
	v_add_f32_e32 v232, v232, v57
	s_waitcnt lgkmcnt(4)
	v_mfma_f32_32x32x16_bf16 v[2:17], v[170:173], v[42:45], v[2:17]
	v_cvt_pk_bf16_f32 v50, v50, v51
	v_cvt_pk_bf16_f32 v51, v52, v53
	v_cvt_pk_bf16_f32 v52, v54, v55
	v_cvt_pk_bf16_f32 v53, v56, v57
	v_exp_f32_e32 v58, v58
	v_mfma_f32_32x32x16_bf16 v[18:33], v[174:177], v[42:45], v[18:33]
	s_waitcnt vmcnt(4)
	ds_write_b64 v225, v[216:217] offset:0
	ds_write_b64 v225, v[218:219] offset:16
	v_exp_f32_e32 v59, v59
	v_exp_f32_e32 v60, v60
	v_exp_f32_e32 v61, v61
	s_waitcnt lgkmcnt(4)
	v_mfma_f32_32x32x16_bf16 v[2:17], v[180:183], v[50:53], v[2:17]
	v_add_f32_e32 v231, v231, v58
	v_add_f32_e32 v232, v232, v59
	v_exp_f32_e32 v62, v62
	v_mfma_f32_32x32x16_bf16 v[18:33], v[184:187], v[50:53], v[18:33]
	v_exp_f32_e32 v63, v63
	v_add_f32_e32 v231, v231, v60
	v_add_f32_e32 v232, v232, v61
	v_exp_f32_e32 v64, v64
	v_exp_f32_e32 v65, v65
	v_add_f32_e32 v231, v231, v62
	v_add_f32_e32 v232, v232, v63
	v_add_f32_e32 v231, v231, v64
	v_add_f32_e32 v232, v232, v65
	v_cvt_pk_bf16_f32 v58, v58, v59
	v_cvt_pk_bf16_f32 v59, v60, v61
	v_cvt_pk_bf16_f32 v60, v62, v63
	v_cvt_pk_bf16_f32 v61, v64, v65
	s_waitcnt lgkmcnt(2)
	s_nop 0
	v_mfma_f32_32x32x16_bf16 v[2:17], v[188:191], v[58:61], v[2:17]
	v_mfma_f32_32x32x16_bf16 v[18:33], v[192:195], v[58:61], v[18:33]
	ds_read_b128 v[138:141], v220 offset:0
	ds_read_b128 v[142:145], v220 offset:6656
	ds_read_b128 v[146:149], v220 offset:32
	ds_read_b128 v[150:153], v220 offset:6688
	ds_read_b128 v[154:157], v220 offset:64
	ds_read_b128 v[158:161], v220 offset:6720
	s_waitcnt lgkmcnt(6)
	v_exp_f32_e32 v66, v66
	v_exp_f32_e32 v67, v67
	v_exp_f32_e32 v68, v68
	s_waitcnt lgkmcnt(4)
	v_mfma_f32_32x32x16_bf16 v[34:49], v[138:141], v[98:101], v[122:137]
	ds_read_b128 v[138:141], v220 offset:96
	v_exp_f32_e32 v69, v69
	v_add_f32_e32 v231, v231, v66
	v_add_f32_e32 v232, v232, v67
	v_exp_f32_e32 v70, v70
	v_mfma_f32_32x32x16_bf16 v[50:65], v[142:145], v[98:101], v[122:137]
	ds_read_b128 v[142:145], v220 offset:6752
	v_exp_f32_e32 v71, v71
	v_add_f32_e32 v231, v231, v68
	v_add_f32_e32 v232, v232, v69
	s_waitcnt lgkmcnt(4)
	v_mfma_f32_32x32x16_bf16 v[34:49], v[146:149], v[102:105], v[34:49]
	ds_read_b128 v[146:149], v220 offset:128
	global_load_dwordx4 v[216:219], v229, s[10:11]
	s_add_u32 s10, s10, 0x80
	s_addc_u32 s11, s11, 0
	v_exp_f32_e32 v72, v72
	v_exp_f32_e32 v73, v73
	v_add_f32_e32 v231, v231, v70
	v_add_f32_e32 v232, v232, v71
	v_mfma_f32_32x32x16_bf16 v[50:65], v[150:153], v[102:105], v[50:65]
	ds_read_b128 v[150:153], v220 offset:6784
	v_add_f32_e32 v231, v231, v72
	v_add_f32_e32 v232, v232, v73
	v_cvt_pk_bf16_f32 v66, v66, v67
	v_cvt_pk_bf16_f32 v67, v68, v69
	v_cvt_pk_bf16_f32 v68, v70, v71
	s_waitcnt lgkmcnt(4)
	v_mfma_f32_32x32x16_bf16 v[34:49], v[154:157], v[106:109], v[34:49]
	ds_read_b128 v[154:157], v220 offset:160
	v_cvt_pk_bf16_f32 v69, v72, v73
	v_exp_f32_e32 v74, v74
	v_exp_f32_e32 v75, v75
	v_mfma_f32_32x32x16_bf16 v[50:65], v[158:161], v[106:109], v[50:65]
	ds_read_b128 v[158:161], v220 offset:6816
	v_exp_f32_e32 v76, v76
	v_exp_f32_e32 v77, v77
	v_add_f32_e32 v231, v231, v74
	v_add_f32_e32 v232, v232, v75
	s_waitcnt lgkmcnt(4)
	v_mfma_f32_32x32x16_bf16 v[34:49], v[138:141], v[110:113], v[34:49]
	ds_read_b128 v[162:165], v221 offset:27648
	v_exp_f32_e32 v78, v78
	v_exp_f32_e32 v79, v79
	v_add_f32_e32 v231, v231, v76
	v_mfma_f32_32x32x16_bf16 v[50:65], v[142:145], v[110:113], v[50:65]
	ds_read_b128 v[166:169], v221 offset:32256
	v_add_f32_e32 v232, v232, v77
	v_exp_f32_e32 v80, v80
	v_exp_f32_e32 v81, v81
	s_waitcnt lgkmcnt(4)
	v_mfma_f32_32x32x16_bf16 v[34:49], v[146:149], v[114:117], v[34:49]
	ds_read_b128 v[170:173], v221 offset:27680
	v_add_f32_e32 v231, v231, v78
	v_add_f32_e32 v232, v232, v79
	v_add_f32_e32 v231, v231, v80
	v_add_f32_e32 v232, v232, v81
	v_cvt_pk_bf16_f32 v74, v74, v75
	v_cvt_pk_bf16_f32 v75, v76, v77
	v_mfma_f32_32x32x16_bf16 v[50:65], v[150:153], v[114:117], v[50:65]
	ds_read_b128 v[174:177], v221 offset:32288
	v_cvt_pk_bf16_f32 v76, v78, v79
	v_cvt_pk_bf16_f32 v77, v80, v81
	v_exp_f32_e32 v82, v82
	v_exp_f32_e32 v83, v83
	s_waitcnt lgkmcnt(4)
	v_mfma_f32_32x32x16_bf16 v[34:49], v[154:157], v[118:121], v[34:49]
	ds_read_b128 v[180:183], v221 offset:27712
	v_exp_f32_e32 v84, v84
	v_exp_f32_e32 v85, v85
	v_mfma_f32_32x32x16_bf16 v[50:65], v[158:161], v[118:121], v[50:65]
	ds_read_b128 v[184:187], v221 offset:32320
	v_add_f32_e32 v231, v231, v82
	v_add_f32_e32 v232, v232, v83
	v_exp_f32_e32 v86, v86
	v_exp_f32_e32 v87, v87
	s_waitcnt lgkmcnt(4)
	v_mfma_f32_32x32x16_bf16 v[2:17], v[162:165], v[66:69], v[2:17]
	ds_read_b128 v[188:191], v221 offset:27744
	v_add_f32_e32 v231, v231, v84
	v_add_f32_e32 v232, v232, v85
	v_exp_f32_e32 v88, v88
	v_exp_f32_e32 v89, v89
	v_mfma_f32_32x32x16_bf16 v[18:33], v[166:169], v[66:69], v[18:33]
	ds_read_b128 v[192:195], v221 offset:32352
	v_add_f32_e32 v231, v231, v86
	v_add_f32_e32 v232, v232, v87
	v_add_f32_e32 v231, v231, v88
	v_add_f32_e32 v232, v232, v89
	s_waitcnt lgkmcnt(4)
	v_mfma_f32_32x32x16_bf16 v[2:17], v[170:173], v[74:77], v[2:17]
	v_cvt_pk_bf16_f32 v82, v82, v83
	v_cvt_pk_bf16_f32 v83, v84, v85
	v_cvt_pk_bf16_f32 v84, v86, v87
	v_cvt_pk_bf16_f32 v85, v88, v89
	v_exp_f32_e32 v90, v90
	v_mfma_f32_32x32x16_bf16 v[18:33], v[174:177], v[74:77], v[18:33]
	s_waitcnt vmcnt(1)
	ds_write_b128 v222, v[200:203] offset:13312
	ds_write_b128 v223, v[204:207] offset:13312
	ds_write_b128 v224, v[208:211] offset:13312
	ds_write_b64 v225, v[212:213] offset:9216
	ds_write_b64 v225, v[214:215] offset:9232
	v_exp_f32_e32 v91, v91
	v_exp_f32_e32 v92, v92
	v_exp_f32_e32 v93, v93
	s_waitcnt lgkmcnt(7)
	v_mfma_f32_32x32x16_bf16 v[2:17], v[180:183], v[82:85], v[2:17]
	v_add_f32_e32 v231, v231, v90
	v_add_f32_e32 v232, v232, v91
	v_exp_f32_e32 v94, v94
	v_mfma_f32_32x32x16_bf16 v[18:33], v[184:187], v[82:85], v[18:33]
	v_exp_f32_e32 v95, v95
	v_add_f32_e32 v231, v231, v92
	v_add_f32_e32 v232, v232, v93
	v_exp_f32_e32 v96, v96
	v_exp_f32_e32 v97, v97
	v_add_f32_e32 v231, v231, v94
	v_add_f32_e32 v232, v232, v95
	v_add_f32_e32 v231, v231, v96
	v_add_f32_e32 v232, v232, v97
	v_cvt_pk_bf16_f32 v90, v90, v91
	v_cvt_pk_bf16_f32 v91, v92, v93
	v_cvt_pk_bf16_f32 v92, v94, v95
	v_cvt_pk_bf16_f32 v93, v96, v97
	s_waitcnt lgkmcnt(5)
	s_nop 0
	v_mfma_f32_32x32x16_bf16 v[2:17], v[188:191], v[90:93], v[2:17]
	v_mfma_f32_32x32x16_bf16 v[18:33], v[192:195], v[90:93], v[18:33]
	s_waitcnt lgkmcnt(0)
	s_barrier
	s_add_i32 s16, s16, -1
	s_cmp_lg_u32 s16, 0
	s_cbranch_scc1 .Lmla_loop
	ds_read_b128 v[138:141], v220 offset:13312
	ds_read_b128 v[142:145], v220 offset:19968
	ds_read_b128 v[146:149], v220 offset:13344
	ds_read_b128 v[150:153], v220 offset:20000
	ds_read_b128 v[154:157], v220 offset:13376
	ds_read_b128 v[158:161], v220 offset:20032
	v_exp_f32_e32 v34, v34
	v_exp_f32_e32 v35, v35
	v_exp_f32_e32 v36, v36
	s_waitcnt lgkmcnt(4)
	v_mfma_f32_32x32x16_bf16 v[66:81], v[138:141], v[98:101], v[122:137]
	ds_read_b128 v[138:141], v220 offset:13408
	v_exp_f32_e32 v37, v37
	v_add_f32_e32 v231, v231, v34
	v_add_f32_e32 v232, v232, v35
	v_exp_f32_e32 v38, v38
	v_mfma_f32_32x32x16_bf16 v[82:97], v[142:145], v[98:101], v[122:137]
	ds_read_b128 v[142:145], v220 offset:20064
	v_exp_f32_e32 v39, v39
	v_add_f32_e32 v231, v231, v36
	v_add_f32_e32 v232, v232, v37
	s_waitcnt lgkmcnt(4)
	v_mfma_f32_32x32x16_bf16 v[66:81], v[146:149], v[102:105], v[66:81]
	ds_read_b128 v[146:149], v220 offset:13440
	global_load_dwordx4 v[200:203], v226, s[4:5]
	global_load_dwordx4 v[204:207], v227, s[4:5]
	global_load_dwordx4 v[208:211], v228, s[4:5]
	s_add_u32 s4, s4, 0x6000
	s_addc_u32 s5, s5, 0
	global_load_dwordx4 v[212:215], v229, s[10:11]
	s_add_u32 s10, s10, 0x80
	s_addc_u32 s11, s11, 0
	v_exp_f32_e32 v40, v40
	v_exp_f32_e32 v41, v41
	v_add_f32_e32 v231, v231, v38
	v_add_f32_e32 v232, v232, v39
	v_mfma_f32_32x32x16_bf16 v[82:97], v[150:153], v[102:105], v[82:97]
	ds_read_b128 v[150:153], v220 offset:20096
	v_add_f32_e32 v231, v231, v40
	v_add_f32_e32 v232, v232, v41
	v_cvt_pk_bf16_f32 v34, v34, v35
	v_cvt_pk_bf16_f32 v35, v36, v37
	v_cvt_pk_bf16_f32 v36, v38, v39
	s_waitcnt lgkmcnt(4)
	v_mfma_f32_32x32x16_bf16 v[66:81], v[154:157], v[106:109], v[66:81]
	ds_read_b128 v[154:157], v220 offset:13472
	v_cvt_pk_bf16_f32 v37, v40, v41
	v_exp_f32_e32 v42, v42
	v_exp_f32_e32 v43, v43
	v_mfma_f32_32x32x16_bf16 v[82:97], v[158:161], v[106:109], v[82:97]
	ds_read_b128 v[158:161], v220 offset:20128
	v_exp_f32_e32 v44, v44
	v_exp_f32_e32 v45, v45
	v_add_f32_e32 v231, v231, v42
	v_add_f32_e32 v232, v232, v43
	s_waitcnt lgkmcnt(4)
	v_mfma_f32_32x32x16_bf16 v[66:81], v[138:141], v[110:113], v[66:81]
	ds_read_b128 v[162:165], v221 offset:0
	v_exp_f32_e32 v46, v46
	v_exp_f32_e32 v47, v47
	v_add_f32_e32 v231, v231, v44
	v_mfma_f32_32x32x16_bf16 v[82:97], v[142:145], v[110:113], v[82:97]
	ds_read_b128 v[166:169], v221 offset:4608
	v_add_f32_e32 v232, v232, v45
	v_exp_f32_e32 v48, v48
	v_exp_f32_e32 v49, v49
	s_waitcnt lgkmcnt(4)
	v_mfma_f32_32x32x16_bf16 v[66:81], v[146:149], v[114:117], v[66:81]
	ds_read_b128 v[170:173], v221 offset:32
	v_add_f32_e32 v231, v231, v46
	v_add_f32_e32 v232, v232, v47
	v_add_f32_e32 v231, v231, v48
	v_add_f32_e32 v232, v232, v49
	v_cvt_pk_bf16_f32 v42, v42, v43
	v_cvt_pk_bf16_f32 v43, v44, v45
	v_mfma_f32_32x32x16_bf16 v[82:97], v[150:153], v[114:117], v[82:97]
	ds_read_b128 v[174:177], v221 offset:4640
	v_cvt_pk_bf16_f32 v44, v46, v47
	v_cvt_pk_bf16_f32 v45, v48, v49
	v_exp_f32_e32 v50, v50
	v_exp_f32_e32 v51, v51
	s_waitcnt lgkmcnt(4)
	v_mfma_f32_32x32x16_bf16 v[66:81], v[154:157], v[118:121], v[66:81]
	ds_read_b128 v[180:183], v221 offset:64
	v_exp_f32_e32 v52, v52
	v_exp_f32_e32 v53, v53
	v_mfma_f32_32x32x16_bf16 v[82:97], v[158:161], v[118:121], v[82:97]
	ds_read_b128 v[184:187], v221 offset:4672
	v_add_f32_e32 v231, v231, v50
	v_add_f32_e32 v232, v232, v51
	v_exp_f32_e32 v54, v54
	v_exp_f32_e32 v55, v55
	s_waitcnt lgkmcnt(4)
	v_mfma_f32_32x32x16_bf16 v[2:17], v[162:165], v[34:37], v[2:17]
	ds_read_b128 v[188:191], v221 offset:96
	v_add_f32_e32 v231, v231, v52
	v_add_f32_e32 v232, v232, v53
	v_exp_f32_e32 v56, v56
	v_exp_f32_e32 v57, v57
	v_mfma_f32_32x32x16_bf16 v[18:33], v[166:169], v[34:37], v[18:33]
	ds_read_b128 v[192:195], v221 offset:4704
	v_add_f32_e32 v231, v231, v54
	v_add_f32_e32 v232, v232, v55
	v_add_f32_e32 v231, v231, v56
	v_add_f32_e32 v232, v232, v57
	s_waitcnt lgkmcnt(4)
	v_mfma_f32_32x32x16_bf16 v[2:17], v[170:173], v[42:45], v[2:17]
	v_cvt_pk_bf16_f32 v50, v50, v51
	v_cvt_pk_bf16_f32 v51, v52, v53
	v_cvt_pk_bf16_f32 v52, v54, v55
	v_cvt_pk_bf16_f32 v53, v56, v57
	v_exp_f32_e32 v58, v58
	v_mfma_f32_32x32x16_bf16 v[18:33], v[174:177], v[42:45], v[18:33]
	s_waitcnt vmcnt(4)
	ds_write_b64 v225, v[216:217] offset:18432
	ds_write_b64 v225, v[218:219] offset:18448
	v_exp_f32_e32 v59, v59
	v_exp_f32_e32 v60, v60
	v_exp_f32_e32 v61, v61
	s_waitcnt lgkmcnt(4)
	v_mfma_f32_32x32x16_bf16 v[2:17], v[180:183], v[50:53], v[2:17]
	v_add_f32_e32 v231, v231, v58
	v_add_f32_e32 v232, v232, v59
	v_exp_f32_e32 v62, v62
	v_mfma_f32_32x32x16_bf16 v[18:33], v[184:187], v[50:53], v[18:33]
	v_exp_f32_e32 v63, v63
	v_add_f32_e32 v231, v231, v60
	v_add_f32_e32 v232, v232, v61
	v_exp_f32_e32 v64, v64
	v_exp_f32_e32 v65, v65
	v_add_f32_e32 v231, v231, v62
	v_add_f32_e32 v232, v232, v63
	v_add_f32_e32 v231, v231, v64
	v_add_f32_e32 v232, v232, v65
	v_cvt_pk_bf16_f32 v58, v58, v59
	v_cvt_pk_bf16_f32 v59, v60, v61
	v_cvt_pk_bf16_f32 v60, v62, v63
	v_cvt_pk_bf16_f32 v61, v64, v65
	s_waitcnt lgkmcnt(2)
	s_nop 0
	v_mfma_f32_32x32x16_bf16 v[2:17], v[188:191], v[58:61], v[2:17]
	v_mfma_f32_32x32x16_bf16 v[18:33], v[192:195], v[58:61], v[18:33]
	ds_read_b128 v[138:141], v220 offset:26624
	ds_read_b128 v[142:145], v220 offset:33280
	ds_read_b128 v[146:149], v220 offset:26656
	ds_read_b128 v[150:153], v220 offset:33312
	ds_read_b128 v[154:157], v220 offset:26688
	ds_read_b128 v[158:161], v220 offset:33344
	s_waitcnt lgkmcnt(6)
	v_exp_f32_e32 v66, v66
	v_exp_f32_e32 v67, v67
	v_exp_f32_e32 v68, v68
	s_waitcnt lgkmcnt(4)
	v_mfma_f32_32x32x16_bf16 v[34:49], v[138:141], v[98:101], v[122:137]
	ds_read_b128 v[138:141], v220 offset:26720
	v_exp_f32_e32 v69, v69
	v_add_f32_e32 v231, v231, v66
	v_add_f32_e32 v232, v232, v67
	v_exp_f32_e32 v70, v70
	v_mfma_f32_32x32x16_bf16 v[50:65], v[142:145], v[98:101], v[122:137]
	ds_read_b128 v[142:145], v220 offset:33376
	v_exp_f32_e32 v71, v71
	v_add_f32_e32 v231, v231, v68
	v_add_f32_e32 v232, v232, v69
	s_waitcnt lgkmcnt(4)
	v_mfma_f32_32x32x16_bf16 v[34:49], v[146:149], v[102:105], v[34:49]
	ds_read_b128 v[146:149], v220 offset:26752
	v_exp_f32_e32 v72, v72
	v_exp_f32_e32 v73, v73
	v_add_f32_e32 v231, v231, v70
	v_add_f32_e32 v232, v232, v71
	v_mfma_f32_32x32x16_bf16 v[50:65], v[150:153], v[102:105], v[50:65]
	ds_read_b128 v[150:153], v220 offset:33408
	v_add_f32_e32 v231, v231, v72
	v_add_f32_e32 v232, v232, v73
	v_cvt_pk_bf16_f32 v66, v66, v67
	v_cvt_pk_bf16_f32 v67, v68, v69
	v_cvt_pk_bf16_f32 v68, v70, v71
	s_waitcnt lgkmcnt(4)
	v_mfma_f32_32x32x16_bf16 v[34:49], v[154:157], v[106:109], v[34:49]
	ds_read_b128 v[154:157], v220 offset:26784
	v_cvt_pk_bf16_f32 v69, v72, v73
	v_exp_f32_e32 v74, v74
	v_exp_f32_e32 v75, v75
	v_mfma_f32_32x32x16_bf16 v[50:65], v[158:161], v[106:109], v[50:65]
	ds_read_b128 v[158:161], v220 offset:33440
	v_exp_f32_e32 v76, v76
	v_exp_f32_e32 v77, v77
	v_add_f32_e32 v231, v231, v74
	v_add_f32_e32 v232, v232, v75
	s_waitcnt lgkmcnt(4)
	v_mfma_f32_32x32x16_bf16 v[34:49], v[138:141], v[110:113], v[34:49]
	ds_read_b128 v[162:165], v221 offset:9216
	v_exp_f32_e32 v78, v78
	v_exp_f32_e32 v79, v79
	v_add_f32_e32 v231, v231, v76
	v_mfma_f32_32x32x16_bf16 v[50:65], v[142:145], v[110:113], v[50:65]
	ds_read_b128 v[166:169], v221 offset:13824
	v_add_f32_e32 v232, v232, v77
	v_exp_f32_e32 v80, v80
	v_exp_f32_e32 v81, v81
	s_waitcnt lgkmcnt(4)
	v_mfma_f32_32x32x16_bf16 v[34:49], v[146:149], v[114:117], v[34:49]
	ds_read_b128 v[170:173], v221 offset:9248
	v_add_f32_e32 v231, v231, v78
	v_add_f32_e32 v232, v232, v79
	v_add_f32_e32 v231, v231, v80
	v_add_f32_e32 v232, v232, v81
	v_cvt_pk_bf16_f32 v74, v74, v75
	v_cvt_pk_bf16_f32 v75, v76, v77
	v_mfma_f32_32x32x16_bf16 v[50:65], v[150:153], v[114:117], v[50:65]
	ds_read_b128 v[174:177], v221 offset:13856
	v_cvt_pk_bf16_f32 v76, v78, v79
	v_cvt_pk_bf16_f32 v77, v80, v81
	v_exp_f32_e32 v82, v82
	v_exp_f32_e32 v83, v83
	s_waitcnt lgkmcnt(4)
	v_mfma_f32_32x32x16_bf16 v[34:49], v[154:157], v[118:121], v[34:49]
	ds_read_b128 v[180:183], v221 offset:9280
	v_exp_f32_e32 v84, v84
	v_exp_f32_e32 v85, v85
	v_mfma_f32_32x32x16_bf16 v[50:65], v[158:161], v[118:121], v[50:65]
	ds_read_b128 v[184:187], v221 offset:13888
	v_add_f32_e32 v231, v231, v82
	v_add_f32_e32 v232, v232, v83
	v_exp_f32_e32 v86, v86
	v_exp_f32_e32 v87, v87
	s_waitcnt lgkmcnt(4)
	v_mfma_f32_32x32x16_bf16 v[2:17], v[162:165], v[66:69], v[2:17]
	ds_read_b128 v[188:191], v221 offset:9312
	v_add_f32_e32 v231, v231, v84
	v_add_f32_e32 v232, v232, v85
	v_exp_f32_e32 v88, v88
	v_exp_f32_e32 v89, v89
	v_mfma_f32_32x32x16_bf16 v[18:33], v[166:169], v[66:69], v[18:33]
	ds_read_b128 v[192:195], v221 offset:13920
	v_add_f32_e32 v231, v231, v86
	v_add_f32_e32 v232, v232, v87
	v_add_f32_e32 v231, v231, v88
	v_add_f32_e32 v232, v232, v89
	s_waitcnt lgkmcnt(4)
	v_mfma_f32_32x32x16_bf16 v[2:17], v[170:173], v[74:77], v[2:17]
	v_cvt_pk_bf16_f32 v82, v82, v83
	v_cvt_pk_bf16_f32 v83, v84, v85
	v_cvt_pk_bf16_f32 v84, v86, v87
	v_cvt_pk_bf16_f32 v85, v88, v89
	v_exp_f32_e32 v90, v90
	v_mfma_f32_32x32x16_bf16 v[18:33], v[174:177], v[74:77], v[18:33]
	s_waitcnt vmcnt(0)
	ds_write_b128 v238, v[200:203]
	ds_write_b128 v239, v[204:207]
	ds_write_b128 v240, v[208:211]
	ds_write_b64 v225, v[212:213] offset:27648
	ds_write_b64 v225, v[214:215] offset:27664
	v_exp_f32_e32 v91, v91
	v_exp_f32_e32 v92, v92
	v_exp_f32_e32 v93, v93
	s_waitcnt lgkmcnt(7)
	v_mfma_f32_32x32x16_bf16 v[2:17], v[180:183], v[82:85], v[2:17]
	v_add_f32_e32 v231, v231, v90
	v_add_f32_e32 v232, v232, v91
	v_exp_f32_e32 v94, v94
	v_mfma_f32_32x32x16_bf16 v[18:33], v[184:187], v[82:85], v[18:33]
	v_exp_f32_e32 v95, v95
	v_add_f32_e32 v231, v231, v92
	v_add_f32_e32 v232, v232, v93
	v_exp_f32_e32 v96, v96
	v_exp_f32_e32 v97, v97
	v_add_f32_e32 v231, v231, v94
	v_add_f32_e32 v232, v232, v95
	v_add_f32_e32 v231, v231, v96
	v_add_f32_e32 v232, v232, v97
	v_cvt_pk_bf16_f32 v90, v90, v91
	v_cvt_pk_bf16_f32 v91, v92, v93
	v_cvt_pk_bf16_f32 v92, v94, v95
	v_cvt_pk_bf16_f32 v93, v96, v97
	s_waitcnt lgkmcnt(5)
	s_nop 0
	v_mfma_f32_32x32x16_bf16 v[2:17], v[188:191], v[90:93], v[2:17]
	v_mfma_f32_32x32x16_bf16 v[18:33], v[192:195], v[90:93], v[18:33]
	s_waitcnt lgkmcnt(0)
	s_barrier
	global_load_dwordx2 v[200:201], v236, s[14:15] offset:0
	global_load_dwordx2 v[202:203], v236, s[14:15] offset:16
	global_load_dwordx2 v[204:205], v236, s[14:15] offset:32
	global_load_dwordx2 v[206:207], v236, s[14:15] offset:48
	global_load_dwordx2 v[208:209], v236, s[14:15] offset:64
	global_load_dwordx2 v[210:211], v236, s[14:15] offset:80
	global_load_dwordx2 v[212:213], v236, s[14:15] offset:96
	global_load_dwordx2 v[214:215], v236, s[14:15] offset:112
	ds_read_b128 v[138:141], v220 offset:39936
	ds_read_b128 v[142:145], v220 offset:46592
	ds_read_b128 v[146:149], v220 offset:39968
	ds_read_b128 v[150:153], v220 offset:46624
	ds_read_b128 v[154:157], v220 offset:40000
	ds_read_b128 v[158:161], v220 offset:46656
	v_exp_f32_e32 v34, v34
	v_exp_f32_e32 v35, v35
	v_exp_f32_e32 v36, v36
	s_waitcnt lgkmcnt(4)
	v_mfma_f32_32x32x16_bf16 v[66:81], v[138:141], v[98:101], v[122:137]
	ds_read_b128 v[138:141], v220 offset:40032
	v_exp_f32_e32 v37, v37
	v_add_f32_e32 v231, v231, v34
	v_add_f32_e32 v232, v232, v35
	v_exp_f32_e32 v38, v38
	v_mfma_f32_32x32x16_bf16 v[82:97], v[142:145], v[98:101], v[122:137]
	ds_read_b128 v[142:145], v220 offset:46688
	v_exp_f32_e32 v39, v39
	v_add_f32_e32 v231, v231, v36
	v_add_f32_e32 v232, v232, v37
	s_waitcnt lgkmcnt(4)
	v_mfma_f32_32x32x16_bf16 v[66:81], v[146:149], v[102:105], v[66:81]
	ds_read_b128 v[146:149], v220 offset:40064
	v_exp_f32_e32 v40, v40
	v_exp_f32_e32 v41, v41
	v_add_f32_e32 v231, v231, v38
	v_add_f32_e32 v232, v232, v39
	v_mfma_f32_32x32x16_bf16 v[82:97], v[150:153], v[102:105], v[82:97]
	ds_read_b128 v[150:153], v220 offset:46720
	v_add_f32_e32 v231, v231, v40
	v_add_f32_e32 v232, v232, v41
	v_cvt_pk_bf16_f32 v34, v34, v35
	v_cvt_pk_bf16_f32 v35, v36, v37
	v_cvt_pk_bf16_f32 v36, v38, v39
	s_waitcnt lgkmcnt(4)
	v_mfma_f32_32x32x16_bf16 v[66:81], v[154:157], v[106:109], v[66:81]
	ds_read_b128 v[154:157], v220 offset:40096
	v_cvt_pk_bf16_f32 v37, v40, v41
	v_exp_f32_e32 v42, v42
	v_exp_f32_e32 v43, v43
	v_mfma_f32_32x32x16_bf16 v[82:97], v[158:161], v[106:109], v[82:97]
	ds_read_b128 v[158:161], v220 offset:46752
	v_exp_f32_e32 v44, v44
	v_exp_f32_e32 v45, v45
	v_add_f32_e32 v231, v231, v42
	v_add_f32_e32 v232, v232, v43
	s_waitcnt lgkmcnt(4)
	v_mfma_f32_32x32x16_bf16 v[66:81], v[138:141], v[110:113], v[66:81]
	ds_read_b128 v[162:165], v221 offset:18432
	v_exp_f32_e32 v46, v46
	v_exp_f32_e32 v47, v47
	v_add_f32_e32 v231, v231, v44
	v_mfma_f32_32x32x16_bf16 v[82:97], v[142:145], v[110:113], v[82:97]
	ds_read_b128 v[166:169], v221 offset:23040
	v_add_f32_e32 v232, v232, v45
	v_exp_f32_e32 v48, v48
	v_exp_f32_e32 v49, v49
	s_waitcnt lgkmcnt(4)
	v_mfma_f32_32x32x16_bf16 v[66:81], v[146:149], v[114:117], v[66:81]
	ds_read_b128 v[170:173], v221 offset:18464
	v_add_f32_e32 v231, v231, v46
	v_add_f32_e32 v232, v232, v47
	v_add_f32_e32 v231, v231, v48
	v_add_f32_e32 v232, v232, v49
	v_cvt_pk_bf16_f32 v42, v42, v43
	v_cvt_pk_bf16_f32 v43, v44, v45
	v_mfma_f32_32x32x16_bf16 v[82:97], v[150:153], v[114:117], v[82:97]
	ds_read_b128 v[174:177], v221 offset:23072
	v_cvt_pk_bf16_f32 v44, v46, v47
	v_cvt_pk_bf16_f32 v45, v48, v49
	v_exp_f32_e32 v50, v50
	v_exp_f32_e32 v51, v51
	s_waitcnt lgkmcnt(4)
	v_mfma_f32_32x32x16_bf16 v[66:81], v[154:157], v[118:121], v[66:81]
	ds_read_b128 v[180:183], v221 offset:18496
	v_exp_f32_e32 v52, v52
	v_exp_f32_e32 v53, v53
	v_mfma_f32_32x32x16_bf16 v[82:97], v[158:161], v[118:121], v[82:97]
	ds_read_b128 v[184:187], v221 offset:23104
	v_add_f32_e32 v231, v231, v50
	v_add_f32_e32 v232, v232, v51
	v_exp_f32_e32 v54, v54
	v_exp_f32_e32 v55, v55
	s_waitcnt lgkmcnt(4)
	v_mfma_f32_32x32x16_bf16 v[2:17], v[162:165], v[34:37], v[2:17]
	ds_read_b128 v[188:191], v221 offset:18528
	v_add_f32_e32 v231, v231, v52
	v_add_f32_e32 v232, v232, v53
	v_exp_f32_e32 v56, v56
	v_exp_f32_e32 v57, v57
	v_mfma_f32_32x32x16_bf16 v[18:33], v[166:169], v[34:37], v[18:33]
	ds_read_b128 v[192:195], v221 offset:23136
	v_add_f32_e32 v231, v231, v54
	v_add_f32_e32 v232, v232, v55
	v_add_f32_e32 v231, v231, v56
	v_add_f32_e32 v232, v232, v57
	s_waitcnt lgkmcnt(4)
	v_mfma_f32_32x32x16_bf16 v[2:17], v[170:173], v[42:45], v[2:17]
	v_cvt_pk_bf16_f32 v50, v50, v51
	v_cvt_pk_bf16_f32 v51, v52, v53
	v_cvt_pk_bf16_f32 v52, v54, v55
	v_cvt_pk_bf16_f32 v53, v56, v57
	v_exp_f32_e32 v58, v58
	v_mfma_f32_32x32x16_bf16 v[18:33], v[174:177], v[42:45], v[18:33]
	v_exp_f32_e32 v59, v59
	v_exp_f32_e32 v60, v60
	v_exp_f32_e32 v61, v61
	s_waitcnt lgkmcnt(2)
	v_mfma_f32_32x32x16_bf16 v[2:17], v[180:183], v[50:53], v[2:17]
	v_add_f32_e32 v231, v231, v58
	v_add_f32_e32 v232, v232, v59
	v_exp_f32_e32 v62, v62
	v_mfma_f32_32x32x16_bf16 v[18:33], v[184:187], v[50:53], v[18:33]
	v_exp_f32_e32 v63, v63
	v_add_f32_e32 v231, v231, v60
	v_add_f32_e32 v232, v232, v61
	v_exp_f32_e32 v64, v64
	v_exp_f32_e32 v65, v65
	v_add_f32_e32 v231, v231, v62
	v_add_f32_e32 v232, v232, v63
	v_add_f32_e32 v231, v231, v64
	v_add_f32_e32 v232, v232, v65
	v_cvt_pk_bf16_f32 v58, v58, v59
	v_cvt_pk_bf16_f32 v59, v60, v61
	v_cvt_pk_bf16_f32 v60, v62, v63
	v_cvt_pk_bf16_f32 v61, v64, v65
	s_waitcnt lgkmcnt(0)
	s_nop 0
	v_mfma_f32_32x32x16_bf16 v[2:17], v[188:191], v[58:61], v[2:17]
	v_mfma_f32_32x32x16_bf16 v[18:33], v[192:195], v[58:61], v[18:33]
	s_waitcnt lgkmcnt(0)
	s_mov_b64 s[24:25], s[14:15]
	s_add_i32 s2, s2, s88
	s_cmpk_lt_i32 s2, 0x200
	s_cbranch_scc0 .Lmla_nopf
	s_lshr_b32 s17, s2, 4
	s_and_b32 s18, s2, 15
	s_mul_i32 s19, s17, 0xcc000
	s_add_u32 s4, s78, s19
	s_addc_u32 s5, s79, 0
	s_mul_i32 s19, s17, 0x88000
	s_add_u32 s19, s19, 0x1a00000
	s_add_u32 s10, s78, s19
	s_addc_u32 s11, s79, 0
	s_lshl_b32 s19, s17, 12
	s_lshl_b32 s20, s18, 8
	s_add_u32 s19, s19, s20
	s_mul_i32 s19, s19, 0xc0
	s_add_u32 s19, s19, 0x1400000
	s_add_u32 s12, s80, s19
	s_addc_u32 s13, s81, 0
	s_lshr_b32 s19, s17, 3
	s_lshl_b32 s19, s19, 12
	s_add_u32 s19, s19, s20
	s_lshl_b32 s19, s19, 10
	s_and_b32 s21, s17, 7
	s_lshl_b32 s21, s21, 7
	s_add_u32 s19, s19, s21
	s_add_u32 s19, s19, 0x7900000
	s_add_u32 s14, s80, s19
	s_addc_u32 s15, s81, 0
	global_load_dwordx4 v[98:101], v237, s[12:13] offset:0
	global_load_dwordx4 v[102:105], v237, s[12:13] offset:32
	global_load_dwordx4 v[106:109], v237, s[12:13] offset:64
	global_load_dwordx4 v[110:113], v237, s[12:13] offset:96
	global_load_dwordx4 v[114:117], v237, s[12:13] offset:128
	global_load_dwordx4 v[118:121], v237, s[12:13] offset:160
	global_load_dwordx4 v[34:37], v226, s[4:5]
	global_load_dwordx4 v[38:41], v227, s[4:5]
	global_load_dwordx4 v[42:45], v228, s[4:5]
	global_load_dwordx4 v[46:49], v229, s[10:11]
	s_add_u32 s4, s4, 0x6000
	s_addc_u32 s5, s5, 0
	global_load_dwordx4 v[50:53], v226, s[4:5]
	global_load_dwordx4 v[54:57], v227, s[4:5]
	global_load_dwordx4 v[58:61], v228, s[4:5]
	global_load_dwordx4 v[62:65], v229, s[10:11] offset:128
	global_load_dwordx4 v[216:219], v229, s[10:11] offset:256
	s_add_u32 s4, s4, 0x3000
	s_addc_u32 s5, s5, 0
	s_add_u32 s10, s10, 0x180
	s_addc_u32 s11, s11, 0

.Lmla_redo:
	s_sub_i32 s2, s2, s88
	s_waitcnt vmcnt(0)
	s_lshr_b32 s17, s2, 4
	s_and_b32 s18, s2, 15
	s_mul_i32 s19, s17, 0xcc000
	s_add_u32 s4, s78, s19
	s_addc_u32 s5, s79, 0
	s_mul_i32 s19, s17, 0x88000
	s_add_u32 s19, s19, 0x1a00000
	s_add_u32 s10, s78, s19
	s_addc_u32 s11, s79, 0
	s_lshl_b32 s19, s17, 12
	s_lshl_b32 s20, s18, 8
	s_add_u32 s19, s19, s20
	s_mul_i32 s19, s19, 0xc0
	s_add_u32 s19, s19, 0x1400000
	s_add_u32 s12, s80, s19
	s_addc_u32 s13, s81, 0
	s_lshr_b32 s19, s17, 3
	s_lshl_b32 s19, s19, 12
	s_add_u32 s19, s19, s20
	s_lshl_b32 s19, s19, 10
	s_and_b32 s21, s17, 7
	s_lshl_b32 s21, s21, 7
	s_add_u32 s19, s19, s21
	s_add_u32 s19, s19, 0x7900000
	s_add_u32 s14, s80, s19
	s_addc_u32 s15, s81, 0
	global_load_dwordx4 v[98:101], v237, s[12:13] offset:0
	global_load_dwordx4 v[102:105], v237, s[12:13] offset:32
	global_load_dwordx4 v[106:109], v237, s[12:13] offset:64
	global_load_dwordx4 v[110:113], v237, s[12:13] offset:96
	global_load_dwordx4 v[114:117], v237, s[12:13] offset:128
	global_load_dwordx4 v[118:121], v237, s[12:13] offset:160
	global_load_dwordx4 v[200:203], v226, s[4:5]
	global_load_dwordx4 v[204:207], v227, s[4:5]
	global_load_dwordx4 v[208:211], v228, s[4:5]
	global_load_dwordx4 v[66:69], v229, s[10:11]
	s_add_u32 s4, s4, 0x6000
	s_addc_u32 s5, s5, 0
	global_load_dwordx4 v[70:73], v226, s[4:5]
	global_load_dwordx4 v[74:77], v227, s[4:5]
	global_load_dwordx4 v[78:81], v228, s[4:5]
	global_load_dwordx4 v[82:85], v229, s[10:11] offset:128
	global_load_dwordx4 v[216:219], v229, s[10:11] offset:256
	s_add_u32 s4, s4, 0x3000
	s_addc_u32 s5, s5, 0
	s_add_u32 s10, s10, 0x180
	s_addc_u32 s11, s11, 0
	v_mov_b32_e32 v2, 0
	v_mov_b32_e32 v3, 0
	v_mov_b32_e32 v4, 0
	v_mov_b32_e32 v5, 0
	v_mov_b32_e32 v6, 0
	v_mov_b32_e32 v7, 0
	v_mov_b32_e32 v8, 0
	v_mov_b32_e32 v9, 0
	v_mov_b32_e32 v10, 0
	v_mov_b32_e32 v11, 0
	v_mov_b32_e32 v12, 0
	v_mov_b32_e32 v13, 0
	v_mov_b32_e32 v14, 0
	v_mov_b32_e32 v15, 0
	v_mov_b32_e32 v16, 0
	v_mov_b32_e32 v17, 0
	v_mov_b32_e32 v18, 0
	v_mov_b32_e32 v19, 0
	v_mov_b32_e32 v20, 0
	v_mov_b32_e32 v21, 0
	v_mov_b32_e32 v22, 0
	v_mov_b32_e32 v23, 0
	v_mov_b32_e32 v24, 0
	v_mov_b32_e32 v25, 0
	v_mov_b32_e32 v26, 0
	v_mov_b32_e32 v27, 0
	v_mov_b32_e32 v28, 0
	v_mov_b32_e32 v29, 0
	v_mov_b32_e32 v30, 0
	v_mov_b32_e32 v31, 0
	v_mov_b32_e32 v32, 0
	v_mov_b32_e32 v33, 0
	v_mov_b32_e32 v122, 0
	v_mov_b32_e32 v123, 0
	v_mov_b32_e32 v124, 0
	v_mov_b32_e32 v125, 0
	v_mov_b32_e32 v126, 0
	v_mov_b32_e32 v127, 0
	v_mov_b32_e32 v128, 0
	v_mov_b32_e32 v129, 0
	v_mov_b32_e32 v130, 0
	v_mov_b32_e32 v131, 0
	v_mov_b32_e32 v132, 0
	v_mov_b32_e32 v133, 0
	v_mov_b32_e32 v134, 0
	v_mov_b32_e32 v135, 0
	v_mov_b32_e32 v136, 0
	v_mov_b32_e32 v137, 0
	v_mov_b32_e32 v230, 0
	v_mov_b32_e32 v231, 0
	v_mov_b32_e32 v232, 0
	s_waitcnt vmcnt(5)
	ds_write_b128 v222, v[200:203]
	ds_write_b128 v223, v[204:207]
	ds_write_b128 v224, v[208:211]
	ds_write_b64 v225, v[66:67]
	ds_write_b64 v225, v[68:69] offset:16
	s_waitcnt vmcnt(1)
	ds_write_b128 v222, v[70:73] offset:26624
	ds_write_b128 v223, v[74:77] offset:26624
	ds_write_b128 v224, v[78:81] offset:26624
	ds_write_b64 v225, v[82:83] offset:9216
	ds_write_b64 v225, v[84:85] offset:9232
	s_waitcnt lgkmcnt(0)
	s_barrier
	ds_read_b128 v[138:141], v220 offset:0
	ds_read_b128 v[142:145], v220 offset:6656
	ds_read_b128 v[146:149], v220 offset:32
	ds_read_b128 v[150:153], v220 offset:6688
	ds_read_b128 v[154:157], v220 offset:64
	ds_read_b128 v[158:161], v220 offset:6720
	ds_read_b128 v[66:69], v220 offset:96
	ds_read_b128 v[70:73], v220 offset:6752
	ds_read_b128 v[74:77], v220 offset:128
	ds_read_b128 v[78:81], v220 offset:6784
	ds_read_b128 v[82:85], v220 offset:160
	ds_read_b128 v[86:89], v220 offset:6816
	s_waitcnt lgkmcnt(11)
	v_mfma_f32_32x32x16_bf16 v[34:49], v[138:141], v[98:101], v[122:137]
	s_waitcnt lgkmcnt(10)
	v_mfma_f32_32x32x16_bf16 v[50:65], v[142:145], v[98:101], v[122:137]
	s_waitcnt lgkmcnt(9)
	v_mfma_f32_32x32x16_bf16 v[34:49], v[146:149], v[102:105], v[34:49]
	s_waitcnt lgkmcnt(8)
	v_mfma_f32_32x32x16_bf16 v[50:65], v[150:153], v[102:105], v[50:65]
	s_waitcnt lgkmcnt(7)
	v_mfma_f32_32x32x16_bf16 v[34:49], v[154:157], v[106:109], v[34:49]
	s_waitcnt lgkmcnt(6)
	v_mfma_f32_32x32x16_bf16 v[50:65], v[158:161], v[106:109], v[50:65]
	s_waitcnt lgkmcnt(5)
	v_mfma_f32_32x32x16_bf16 v[34:49], v[66:69], v[110:113], v[34:49]
	s_waitcnt lgkmcnt(4)
	v_mfma_f32_32x32x16_bf16 v[50:65], v[70:73], v[110:113], v[50:65]
	s_waitcnt lgkmcnt(3)
	v_mfma_f32_32x32x16_bf16 v[34:49], v[74:77], v[114:117], v[34:49]
	s_waitcnt lgkmcnt(2)
	v_mfma_f32_32x32x16_bf16 v[50:65], v[78:81], v[114:117], v[50:65]
	s_waitcnt lgkmcnt(1)
	v_mfma_f32_32x32x16_bf16 v[34:49], v[82:85], v[118:121], v[34:49]
	s_waitcnt lgkmcnt(0)
	v_mfma_f32_32x32x16_bf16 v[50:65], v[86:89], v[118:121], v[50:65]
	s_barrier
	s_nop 15
	v_max3_f32 v234, v34, v35, v36
	v_max3_f32 v235, v50, v51, v52
	v_max3_f32 v234, v234, v37, v38
	v_max3_f32 v235, v235, v53, v54
	v_max3_f32 v234, v234, v39, v40
	v_max3_f32 v235, v235, v55, v56
	v_max3_f32 v234, v234, v41, v42
	v_max3_f32 v235, v235, v57, v58
	v_max3_f32 v234, v234, v43, v44
	v_max3_f32 v235, v235, v59, v60
	v_max3_f32 v234, v234, v45, v46
	v_max3_f32 v235, v235, v61, v62
	v_max3_f32 v234, v234, v47, v48
	v_max3_f32 v235, v235, v63, v64
	v_max3_f32 v234, v234, v49, v65
	v_max_f32_e32 v234, v234, v235
	v_mov_b32_e32 v235, v234
	s_nop 1
	v_permlane32_swap_b32_e32 v234, v235
	v_max_f32_e32 v233, v234, v235
	s_nop 15
	v_add_f32_e32 v230, v230, v233
	v_sub_f32_e32 v34, v34, v233
	v_sub_f32_e32 v35, v35, v233
	v_sub_f32_e32 v36, v36, v233
	v_sub_f32_e32 v37, v37, v233
	v_sub_f32_e32 v38, v38, v233
	v_sub_f32_e32 v39, v39, v233
	v_sub_f32_e32 v40, v40, v233
	v_sub_f32_e32 v41, v41, v233
	v_sub_f32_e32 v42, v42, v233
	v_sub_f32_e32 v43, v43, v233
	v_sub_f32_e32 v44, v44, v233
	v_sub_f32_e32 v45, v45, v233
	v_sub_f32_e32 v46, v46, v233
	v_sub_f32_e32 v47, v47, v233
	v_sub_f32_e32 v48, v48, v233
	v_sub_f32_e32 v49, v49, v233
	v_sub_f32_e32 v50, v50, v233
	v_sub_f32_e32 v51, v51, v233
	v_sub_f32_e32 v52, v52, v233
	v_sub_f32_e32 v53, v53, v233
	v_sub_f32_e32 v54, v54, v233
	v_sub_f32_e32 v55, v55, v233
	v_sub_f32_e32 v56, v56, v233
	v_sub_f32_e32 v57, v57, v233
	v_sub_f32_e32 v58, v58, v233
	v_sub_f32_e32 v59, v59, v233
	v_sub_f32_e32 v60, v60, v233
	v_sub_f32_e32 v61, v61, v233
	v_sub_f32_e32 v62, v62, v233
	v_sub_f32_e32 v63, v63, v233
	v_sub_f32_e32 v64, v64, v233
	v_sub_f32_e32 v65, v65, v233
	v_sub_f32_e32 v122, 0, v230
	v_mov_b32_e32 v123, v122
	v_mov_b32_e32 v124, v122
	v_mov_b32_e32 v125, v122
	v_mov_b32_e32 v126, v122
	v_mov_b32_e32 v127, v122
	v_mov_b32_e32 v128, v122
	v_mov_b32_e32 v129, v122
	v_mov_b32_e32 v130, v122
	v_mov_b32_e32 v131, v122
	v_mov_b32_e32 v132, v122
	v_mov_b32_e32 v133, v122
	v_mov_b32_e32 v134, v122
	v_mov_b32_e32 v135, v122
	v_mov_b32_e32 v136, v122
	v_mov_b32_e32 v137, v122
	s_movk_i32 s16, 16
.Lmls_loop:
	ds_read_b128 v[138:141], v220 offset:13312
	ds_read_b128 v[142:145], v220 offset:19968
	ds_read_b128 v[146:149], v220 offset:13344
	ds_read_b128 v[150:153], v220 offset:20000
	ds_read_b128 v[154:157], v220 offset:13376
	ds_read_b128 v[158:161], v220 offset:20032
	v_exp_f32_e32 v34, v34
	v_exp_f32_e32 v35, v35
	v_exp_f32_e32 v36, v36
	v_exp_f32_e32 v37, v37
	s_waitcnt lgkmcnt(4)
	v_mfma_f32_32x32x16_bf16 v[66:81], v[138:141], v[98:101], v[122:137]
	ds_read_b128 v[138:141], v220 offset:13408
	v_add_f32_e32 v231, v231, v34
	v_add_f32_e32 v232, v232, v35
	v_exp_f32_e32 v38, v38
	v_exp_f32_e32 v39, v39
	v_mfma_f32_32x32x16_bf16 v[82:97], v[142:145], v[98:101], v[122:137]
	ds_read_b128 v[142:145], v220 offset:20064
	v_add_f32_e32 v231, v231, v36
	v_add_f32_e32 v232, v232, v37
	v_exp_f32_e32 v40, v40
	v_exp_f32_e32 v41, v41
	s_waitcnt lgkmcnt(4)
	v_mfma_f32_32x32x16_bf16 v[66:81], v[146:149], v[102:105], v[66:81]
	ds_read_b128 v[146:149], v220 offset:13440
	global_load_dwordx4 v[200:203], v226, s[4:5]
	global_load_dwordx4 v[204:207], v227, s[4:5]
	global_load_dwordx4 v[208:211], v228, s[4:5]
	s_add_u32 s4, s4, 0x6000
	s_addc_u32 s5, s5, 0
	global_load_dwordx4 v[212:215], v229, s[10:11]
	s_add_u32 s10, s10, 0x80
	s_addc_u32 s11, s11, 0
	v_add_f32_e32 v231, v231, v38
	v_add_f32_e32 v232, v232, v39
	v_add_f32_e32 v231, v231, v40
	v_add_f32_e32 v232, v232, v41
	v_cvt_pk_bf16_f32 v34, v34, v35
	v_cvt_pk_bf16_f32 v35, v36, v37
	v_mfma_f32_32x32x16_bf16 v[82:97], v[150:153], v[102:105], v[82:97]
	ds_read_b128 v[150:153], v220 offset:20096
	v_cvt_pk_bf16_f32 v36, v38, v39
	v_cvt_pk_bf16_f32 v37, v40, v41
	v_exp_f32_e32 v42, v42
	v_exp_f32_e32 v43, v43
	s_waitcnt lgkmcnt(4)
	v_mfma_f32_32x32x16_bf16 v[66:81], v[154:157], v[106:109], v[66:81]
	ds_read_b128 v[154:157], v220 offset:13472
	v_exp_f32_e32 v44, v44
	v_exp_f32_e32 v45, v45
	v_add_f32_e32 v231, v231, v42
	v_add_f32_e32 v232, v232, v43
	v_mfma_f32_32x32x16_bf16 v[82:97], v[158:161], v[106:109], v[82:97]
	ds_read_b128 v[158:161], v220 offset:20128
	v_exp_f32_e32 v46, v46
	v_exp_f32_e32 v47, v47
	v_add_f32_e32 v231, v231, v44
	v_add_f32_e32 v232, v232, v45
	v_exp_f32_e32 v48, v48
	s_waitcnt lgkmcnt(4)
	v_mfma_f32_32x32x16_bf16 v[66:81], v[138:141], v[110:113], v[66:81]
	ds_read_b128 v[162:165], v221 offset:0
	v_exp_f32_e32 v49, v49
	v_add_f32_e32 v231, v231, v46
	v_add_f32_e32 v232, v232, v47
	v_add_f32_e32 v231, v231, v48
	v_mfma_f32_32x32x16_bf16 v[82:97], v[142:145], v[110:113], v[82:97]
	ds_read_b128 v[166:169], v221 offset:4608
	v_add_f32_e32 v232, v232, v49
	v_cvt_pk_bf16_f32 v42, v42, v43
	v_cvt_pk_bf16_f32 v43, v44, v45
	v_cvt_pk_bf16_f32 v44, v46, v47
	v_cvt_pk_bf16_f32 v45, v48, v49
	v_exp_f32_e32 v50, v50
	s_waitcnt lgkmcnt(4)
	v_mfma_f32_32x32x16_bf16 v[66:81], v[146:149], v[114:117], v[66:81]
	ds_read_b128 v[170:173], v221 offset:32
	v_exp_f32_e32 v51, v51
	v_exp_f32_e32 v52, v52
	v_exp_f32_e32 v53, v53
	v_mfma_f32_32x32x16_bf16 v[82:97], v[150:153], v[114:117], v[82:97]
	ds_read_b128 v[174:177], v221 offset:4640
	v_add_f32_e32 v231, v231, v50
	v_add_f32_e32 v232, v232, v51
	v_exp_f32_e32 v54, v54
	v_exp_f32_e32 v55, v55
	s_waitcnt lgkmcnt(4)
	v_mfma_f32_32x32x16_bf16 v[66:81], v[154:157], v[118:121], v[66:81]
	ds_read_b128 v[180:183], v221 offset:64
	v_add_f32_e32 v231, v231, v52
	v_add_f32_e32 v232, v232, v53
	v_exp_f32_e32 v56, v56
	v_exp_f32_e32 v57, v57
	v_mfma_f32_32x32x16_bf16 v[82:97], v[158:161], v[118:121], v[82:97]
	ds_read_b128 v[184:187], v221 offset:4672
	v_add_f32_e32 v231, v231, v54
	v_add_f32_e32 v232, v232, v55
	v_add_f32_e32 v231, v231, v56
	v_add_f32_e32 v232, v232, v57
	v_cvt_pk_bf16_f32 v50, v50, v51
	v_cvt_pk_bf16_f32 v51, v52, v53
	v_cvt_pk_bf16_f32 v52, v54, v55
	s_waitcnt lgkmcnt(4)
	v_mfma_f32_32x32x16_bf16 v[2:17], v[162:165], v[34:37], v[2:17]
	ds_read_b128 v[188:191], v221 offset:96
	v_cvt_pk_bf16_f32 v53, v56, v57
	v_exp_f32_e32 v58, v58
	v_exp_f32_e32 v59, v59
	v_exp_f32_e32 v60, v60
	v_mfma_f32_32x32x16_bf16 v[18:33], v[166:169], v[34:37], v[18:33]
	ds_read_b128 v[192:195], v221 offset:4704
	v_exp_f32_e32 v61, v61
	v_add_f32_e32 v231, v231, v58
	v_add_f32_e32 v232, v232, v59
	v_exp_f32_e32 v62, v62
	s_waitcnt lgkmcnt(4)
	v_mfma_f32_32x32x16_bf16 v[2:17], v[170:173], v[42:45], v[2:17]
	v_exp_f32_e32 v63, v63
	v_add_f32_e32 v231, v231, v60
	v_add_f32_e32 v232, v232, v61
	v_exp_f32_e32 v64, v64
	v_mfma_f32_32x32x16_bf16 v[18:33], v[174:177], v[42:45], v[18:33]
	s_waitcnt vmcnt(4)
	ds_write_b64 v225, v[216:217] offset:18432
	ds_write_b64 v225, v[218:219] offset:18448
	v_exp_f32_e32 v65, v65
	v_add_f32_e32 v231, v231, v62
	v_add_f32_e32 v232, v232, v63
	v_add_f32_e32 v231, v231, v64
	v_add_f32_e32 v232, v232, v65
	s_waitcnt lgkmcnt(4)
	v_mfma_f32_32x32x16_bf16 v[2:17], v[180:183], v[50:53], v[2:17]
	v_cvt_pk_bf16_f32 v58, v58, v59
	v_cvt_pk_bf16_f32 v59, v60, v61
	v_cvt_pk_bf16_f32 v60, v62, v63
	v_cvt_pk_bf16_f32 v61, v64, v65
	v_max3_f32 v234, v66, v67, v68
	v_max3_f32 v235, v82, v83, v84
	v_mfma_f32_32x32x16_bf16 v[18:33], v[184:187], v[50:53], v[18:33]
	v_max3_f32 v234, v234, v69, v70
	v_max3_f32 v235, v235, v85, v86
	v_max3_f32 v234, v234, v71, v72
	v_max3_f32 v235, v235, v87, v88
	v_max3_f32 v234, v234, v73, v74
	v_max3_f32 v235, v235, v89, v90
	v_max3_f32 v234, v234, v75, v76
	s_waitcnt lgkmcnt(2)
	v_mfma_f32_32x32x16_bf16 v[2:17], v[188:191], v[58:61], v[2:17]
	v_max3_f32 v235, v235, v91, v92
	v_max3_f32 v234, v234, v77, v78
	v_max3_f32 v235, v235, v93, v94
	v_max3_f32 v234, v234, v79, v80
	v_max3_f32 v235, v235, v95, v96
	v_max3_f32 v234, v234, v81, v97
	v_mfma_f32_32x32x16_bf16 v[18:33], v[192:195], v[58:61], v[18:33]
	v_max_f32_e32 v234, v234, v235
	v_mov_b32_e32 v235, v234
	s_nop 1
	v_permlane32_swap_b32_e32 v234, v235
	v_max_f32_e32 v233, v234, v235
	v_cmp_lt_f32_e32 vcc, 4.0, v233
	s_cbranch_vccz .Lmls_nr_p0
	s_nop 15
	v_max_f32_e32 v234, 0, v233
	v_exp_f32_e64 v235, -v234
	v_add_f32_e32 v230, v230, v234
	v_sub_f32_e32 v66, v66, v234
	v_sub_f32_e32 v67, v67, v234
	v_sub_f32_e32 v68, v68, v234
	v_sub_f32_e32 v69, v69, v234
	v_sub_f32_e32 v70, v70, v234
	v_sub_f32_e32 v71, v71, v234
	v_sub_f32_e32 v72, v72, v234
	v_sub_f32_e32 v73, v73, v234
	v_sub_f32_e32 v74, v74, v234
	v_sub_f32_e32 v75, v75, v234
	v_sub_f32_e32 v76, v76, v234
	v_sub_f32_e32 v77, v77, v234
	v_sub_f32_e32 v78, v78, v234
	v_sub_f32_e32 v79, v79, v234
	v_sub_f32_e32 v80, v80, v234
	v_sub_f32_e32 v81, v81, v234
	v_sub_f32_e32 v82, v82, v234
	v_sub_f32_e32 v83, v83, v234
	v_sub_f32_e32 v84, v84, v234
	v_sub_f32_e32 v85, v85, v234
	v_sub_f32_e32 v86, v86, v234
	v_sub_f32_e32 v87, v87, v234
	v_sub_f32_e32 v88, v88, v234
	v_sub_f32_e32 v89, v89, v234
	v_sub_f32_e32 v90, v90, v234
	v_sub_f32_e32 v91, v91, v234
	v_sub_f32_e32 v92, v92, v234
	v_sub_f32_e32 v93, v93, v234
	v_sub_f32_e32 v94, v94, v234
	v_sub_f32_e32 v95, v95, v234
	v_sub_f32_e32 v96, v96, v234
	v_sub_f32_e32 v97, v97, v234
	v_mul_f32_e32 v231, v231, v235
	v_mul_f32_e32 v232, v232, v235
	v_mul_f32_e32 v2, v2, v235
	v_mul_f32_e32 v3, v3, v235
	v_mul_f32_e32 v4, v4, v235
	v_mul_f32_e32 v5, v5, v235
	v_mul_f32_e32 v6, v6, v235
	v_mul_f32_e32 v7, v7, v235
	v_mul_f32_e32 v8, v8, v235
	v_mul_f32_e32 v9, v9, v235
	v_mul_f32_e32 v10, v10, v235
	v_mul_f32_e32 v11, v11, v235
	v_mul_f32_e32 v12, v12, v235
	v_mul_f32_e32 v13, v13, v235
	v_mul_f32_e32 v14, v14, v235
	v_mul_f32_e32 v15, v15, v235
	v_mul_f32_e32 v16, v16, v235
	v_mul_f32_e32 v17, v17, v235
	v_mul_f32_e32 v18, v18, v235
	v_mul_f32_e32 v19, v19, v235
	v_mul_f32_e32 v20, v20, v235
	v_mul_f32_e32 v21, v21, v235
	v_mul_f32_e32 v22, v22, v235
	v_mul_f32_e32 v23, v23, v235
	v_mul_f32_e32 v24, v24, v235
	v_mul_f32_e32 v25, v25, v235
	v_mul_f32_e32 v26, v26, v235
	v_mul_f32_e32 v27, v27, v235
	v_mul_f32_e32 v28, v28, v235
	v_mul_f32_e32 v29, v29, v235
	v_mul_f32_e32 v30, v30, v235
	v_mul_f32_e32 v31, v31, v235
	v_mul_f32_e32 v32, v32, v235
	v_mul_f32_e32 v33, v33, v235
	v_sub_f32_e32 v122, 0, v230
	v_mov_b32_e32 v123, v122
	v_mov_b32_e32 v124, v122
	v_mov_b32_e32 v125, v122
	v_mov_b32_e32 v126, v122
	v_mov_b32_e32 v127, v122
	v_mov_b32_e32 v128, v122
	v_mov_b32_e32 v129, v122
	v_mov_b32_e32 v130, v122
	v_mov_b32_e32 v131, v122
	v_mov_b32_e32 v132, v122
	v_mov_b32_e32 v133, v122
	v_mov_b32_e32 v134, v122
	v_mov_b32_e32 v135, v122
	v_mov_b32_e32 v136, v122
	v_mov_b32_e32 v137, v122
.Lmls_nr_p0:
	ds_read_b128 v[138:141], v220 offset:26624
	ds_read_b128 v[142:145], v220 offset:33280
	ds_read_b128 v[146:149], v220 offset:26656
	ds_read_b128 v[150:153], v220 offset:33312
	ds_read_b128 v[154:157], v220 offset:26688
	ds_read_b128 v[158:161], v220 offset:33344
	s_waitcnt lgkmcnt(6)
	v_exp_f32_e32 v66, v66
	v_exp_f32_e32 v67, v67
	v_exp_f32_e32 v68, v68
	v_exp_f32_e32 v69, v69
	s_waitcnt lgkmcnt(4)
	v_mfma_f32_32x32x16_bf16 v[34:49], v[138:141], v[98:101], v[122:137]
	ds_read_b128 v[138:141], v220 offset:26720
	v_add_f32_e32 v231, v231, v66
	v_add_f32_e32 v232, v232, v67
	v_exp_f32_e32 v70, v70
	v_exp_f32_e32 v71, v71
	v_mfma_f32_32x32x16_bf16 v[50:65], v[142:145], v[98:101], v[122:137]
	ds_read_b128 v[142:145], v220 offset:33376
	v_add_f32_e32 v231, v231, v68
	v_add_f32_e32 v232, v232, v69
	v_exp_f32_e32 v72, v72
	v_exp_f32_e32 v73, v73
	s_waitcnt lgkmcnt(4)
	v_mfma_f32_32x32x16_bf16 v[34:49], v[146:149], v[102:105], v[34:49]
	ds_read_b128 v[146:149], v220 offset:26752
	global_load_dwordx4 v[216:219], v229, s[10:11]
	s_add_u32 s10, s10, 0x80
	s_addc_u32 s11, s11, 0
	v_add_f32_e32 v231, v231, v70
	v_add_f32_e32 v232, v232, v71
	v_add_f32_e32 v231, v231, v72
	v_add_f32_e32 v232, v232, v73
	v_cvt_pk_bf16_f32 v66, v66, v67
	v_cvt_pk_bf16_f32 v67, v68, v69
	v_mfma_f32_32x32x16_bf16 v[50:65], v[150:153], v[102:105], v[50:65]
	ds_read_b128 v[150:153], v220 offset:33408
	v_cvt_pk_bf16_f32 v68, v70, v71
	v_cvt_pk_bf16_f32 v69, v72, v73
	v_exp_f32_e32 v74, v74
	v_exp_f32_e32 v75, v75
	s_waitcnt lgkmcnt(4)
	v_mfma_f32_32x32x16_bf16 v[34:49], v[154:157], v[106:109], v[34:49]
	ds_read_b128 v[154:157], v220 offset:26784
	v_exp_f32_e32 v76, v76
	v_exp_f32_e32 v77, v77
	v_add_f32_e32 v231, v231, v74
	v_add_f32_e32 v232, v232, v75
	v_mfma_f32_32x32x16_bf16 v[50:65], v[158:161], v[106:109], v[50:65]
	ds_read_b128 v[158:161], v220 offset:33440
	v_exp_f32_e32 v78, v78
	v_exp_f32_e32 v79, v79
	v_add_f32_e32 v231, v231, v76
	v_add_f32_e32 v232, v232, v77
	v_exp_f32_e32 v80, v80
	s_waitcnt lgkmcnt(4)
	v_mfma_f32_32x32x16_bf16 v[34:49], v[138:141], v[110:113], v[34:49]
	ds_read_b128 v[162:165], v221 offset:9216
	v_exp_f32_e32 v81, v81
	v_add_f32_e32 v231, v231, v78
	v_add_f32_e32 v232, v232, v79
	v_add_f32_e32 v231, v231, v80
	v_mfma_f32_32x32x16_bf16 v[50:65], v[142:145], v[110:113], v[50:65]
	ds_read_b128 v[166:169], v221 offset:13824
	v_add_f32_e32 v232, v232, v81
	v_cvt_pk_bf16_f32 v74, v74, v75
	v_cvt_pk_bf16_f32 v75, v76, v77
	v_cvt_pk_bf16_f32 v76, v78, v79
	v_cvt_pk_bf16_f32 v77, v80, v81
	v_exp_f32_e32 v82, v82
	s_waitcnt lgkmcnt(4)
	v_mfma_f32_32x32x16_bf16 v[34:49], v[146:149], v[114:117], v[34:49]
	ds_read_b128 v[170:173], v221 offset:9248
	v_exp_f32_e32 v83, v83
	v_exp_f32_e32 v84, v84
	v_exp_f32_e32 v85, v85
	v_mfma_f32_32x32x16_bf16 v[50:65], v[150:153], v[114:117], v[50:65]
	ds_read_b128 v[174:177], v221 offset:13856
	v_add_f32_e32 v231, v231, v82
	v_add_f32_e32 v232, v232, v83
	v_exp_f32_e32 v86, v86
	v_exp_f32_e32 v87, v87
	s_waitcnt lgkmcnt(4)
	v_mfma_f32_32x32x16_bf16 v[34:49], v[154:157], v[118:121], v[34:49]
	ds_read_b128 v[180:183], v221 offset:9280
	v_add_f32_e32 v231, v231, v84
	v_add_f32_e32 v232, v232, v85
	v_exp_f32_e32 v88, v88
	v_exp_f32_e32 v89, v89
	v_mfma_f32_32x32x16_bf16 v[50:65], v[158:161], v[118:121], v[50:65]
	ds_read_b128 v[184:187], v221 offset:13888
	v_add_f32_e32 v231, v231, v86
	v_add_f32_e32 v232, v232, v87
	v_add_f32_e32 v231, v231, v88
	v_add_f32_e32 v232, v232, v89
	v_cvt_pk_bf16_f32 v82, v82, v83
	v_cvt_pk_bf16_f32 v83, v84, v85
	v_cvt_pk_bf16_f32 v84, v86, v87
	s_waitcnt lgkmcnt(4)
	v_mfma_f32_32x32x16_bf16 v[2:17], v[162:165], v[66:69], v[2:17]
	ds_read_b128 v[188:191], v221 offset:9312
	v_cvt_pk_bf16_f32 v85, v88, v89
	v_exp_f32_e32 v90, v90
	v_exp_f32_e32 v91, v91
	v_exp_f32_e32 v92, v92
	v_mfma_f32_32x32x16_bf16 v[18:33], v[166:169], v[66:69], v[18:33]
	ds_read_b128 v[192:195], v221 offset:13920
	v_exp_f32_e32 v93, v93
	v_add_f32_e32 v231, v231, v90
	v_add_f32_e32 v232, v232, v91
	v_exp_f32_e32 v94, v94
	s_waitcnt lgkmcnt(4)
	v_mfma_f32_32x32x16_bf16 v[2:17], v[170:173], v[74:77], v[2:17]
	v_exp_f32_e32 v95, v95
	v_add_f32_e32 v231, v231, v92
	v_add_f32_e32 v232, v232, v93
	v_exp_f32_e32 v96, v96
	v_mfma_f32_32x32x16_bf16 v[18:33], v[174:177], v[74:77], v[18:33]
	s_waitcnt vmcnt(1)
	ds_write_b128 v238, v[200:203]
	ds_write_b128 v239, v[204:207]
	ds_write_b128 v240, v[208:211]
	ds_write_b64 v225, v[212:213] offset:27648
	ds_write_b64 v225, v[214:215] offset:27664
	v_exp_f32_e32 v97, v97
	v_add_f32_e32 v231, v231, v94
	v_add_f32_e32 v232, v232, v95
	v_add_f32_e32 v231, v231, v96
	v_add_f32_e32 v232, v232, v97
	s_waitcnt lgkmcnt(7)
	v_mfma_f32_32x32x16_bf16 v[2:17], v[180:183], v[82:85], v[2:17]
	v_cvt_pk_bf16_f32 v90, v90, v91
	v_cvt_pk_bf16_f32 v91, v92, v93
	v_cvt_pk_bf16_f32 v92, v94, v95
	v_cvt_pk_bf16_f32 v93, v96, v97
	v_max3_f32 v234, v34, v35, v36
	v_max3_f32 v235, v50, v51, v52
	v_mfma_f32_32x32x16_bf16 v[18:33], v[184:187], v[82:85], v[18:33]
	v_max3_f32 v234, v234, v37, v38
	v_max3_f32 v235, v235, v53, v54
	v_max3_f32 v234, v234, v39, v40
	v_max3_f32 v235, v235, v55, v56
	v_max3_f32 v234, v234, v41, v42
	v_max3_f32 v235, v235, v57, v58
	v_max3_f32 v234, v234, v43, v44
	s_waitcnt lgkmcnt(5)
	v_mfma_f32_32x32x16_bf16 v[2:17], v[188:191], v[90:93], v[2:17]
	v_max3_f32 v235, v235, v59, v60
	v_max3_f32 v234, v234, v45, v46
	v_max3_f32 v235, v235, v61, v62
	v_max3_f32 v234, v234, v47, v48
	v_max3_f32 v235, v235, v63, v64
	v_max3_f32 v234, v234, v49, v65
	v_mfma_f32_32x32x16_bf16 v[18:33], v[192:195], v[90:93], v[18:33]
	v_max_f32_e32 v234, v234, v235
	v_mov_b32_e32 v235, v234
	s_nop 1
	v_permlane32_swap_b32_e32 v234, v235
	v_max_f32_e32 v233, v234, v235
	v_cmp_lt_f32_e32 vcc, 4.0, v233
	s_cbranch_vccz .Lmls_nr_p1
	s_nop 15
	v_max_f32_e32 v234, 0, v233
	v_exp_f32_e64 v235, -v234
	v_add_f32_e32 v230, v230, v234
	v_sub_f32_e32 v34, v34, v234
	v_sub_f32_e32 v35, v35, v234
	v_sub_f32_e32 v36, v36, v234
	v_sub_f32_e32 v37, v37, v234
	v_sub_f32_e32 v38, v38, v234
	v_sub_f32_e32 v39, v39, v234
	v_sub_f32_e32 v40, v40, v234
	v_sub_f32_e32 v41, v41, v234
	v_sub_f32_e32 v42, v42, v234
	v_sub_f32_e32 v43, v43, v234
	v_sub_f32_e32 v44, v44, v234
	v_sub_f32_e32 v45, v45, v234
	v_sub_f32_e32 v46, v46, v234
	v_sub_f32_e32 v47, v47, v234
	v_sub_f32_e32 v48, v48, v234
	v_sub_f32_e32 v49, v49, v234
	v_sub_f32_e32 v50, v50, v234
	v_sub_f32_e32 v51, v51, v234
	v_sub_f32_e32 v52, v52, v234
	v_sub_f32_e32 v53, v53, v234
	v_sub_f32_e32 v54, v54, v234
	v_sub_f32_e32 v55, v55, v234
	v_sub_f32_e32 v56, v56, v234
	v_sub_f32_e32 v57, v57, v234
	v_sub_f32_e32 v58, v58, v234
	v_sub_f32_e32 v59, v59, v234
	v_sub_f32_e32 v60, v60, v234
	v_sub_f32_e32 v61, v61, v234
	v_sub_f32_e32 v62, v62, v234
	v_sub_f32_e32 v63, v63, v234
	v_sub_f32_e32 v64, v64, v234
	v_sub_f32_e32 v65, v65, v234
	v_mul_f32_e32 v231, v231, v235
	v_mul_f32_e32 v232, v232, v235
	v_mul_f32_e32 v2, v2, v235
	v_mul_f32_e32 v3, v3, v235
	v_mul_f32_e32 v4, v4, v235
	v_mul_f32_e32 v5, v5, v235
	v_mul_f32_e32 v6, v6, v235
	v_mul_f32_e32 v7, v7, v235
	v_mul_f32_e32 v8, v8, v235
	v_mul_f32_e32 v9, v9, v235
	v_mul_f32_e32 v10, v10, v235
	v_mul_f32_e32 v11, v11, v235
	v_mul_f32_e32 v12, v12, v235
	v_mul_f32_e32 v13, v13, v235
	v_mul_f32_e32 v14, v14, v235
	v_mul_f32_e32 v15, v15, v235
	v_mul_f32_e32 v16, v16, v235
	v_mul_f32_e32 v17, v17, v235
	v_mul_f32_e32 v18, v18, v235
	v_mul_f32_e32 v19, v19, v235
	v_mul_f32_e32 v20, v20, v235
	v_mul_f32_e32 v21, v21, v235
	v_mul_f32_e32 v22, v22, v235
	v_mul_f32_e32 v23, v23, v235
	v_mul_f32_e32 v24, v24, v235
	v_mul_f32_e32 v25, v25, v235
	v_mul_f32_e32 v26, v26, v235
	v_mul_f32_e32 v27, v27, v235
	v_mul_f32_e32 v28, v28, v235
	v_mul_f32_e32 v29, v29, v235
	v_mul_f32_e32 v30, v30, v235
	v_mul_f32_e32 v31, v31, v235
	v_mul_f32_e32 v32, v32, v235
	v_mul_f32_e32 v33, v33, v235
	v_sub_f32_e32 v122, 0, v230
	v_mov_b32_e32 v123, v122
	v_mov_b32_e32 v124, v122
	v_mov_b32_e32 v125, v122
	v_mov_b32_e32 v126, v122
	v_mov_b32_e32 v127, v122
	v_mov_b32_e32 v128, v122
	v_mov_b32_e32 v129, v122
	v_mov_b32_e32 v130, v122
	v_mov_b32_e32 v131, v122
	v_mov_b32_e32 v132, v122
	v_mov_b32_e32 v133, v122
	v_mov_b32_e32 v134, v122
	v_mov_b32_e32 v135, v122
	v_mov_b32_e32 v136, v122
	v_mov_b32_e32 v137, v122
.Lmls_nr_p1:
	s_waitcnt lgkmcnt(0)
	s_barrier
	ds_read_b128 v[138:141], v220 offset:39936
	ds_read_b128 v[142:145], v220 offset:46592
	ds_read_b128 v[146:149], v220 offset:39968
	ds_read_b128 v[150:153], v220 offset:46624
	ds_read_b128 v[154:157], v220 offset:40000
	ds_read_b128 v[158:161], v220 offset:46656
	v_exp_f32_e32 v34, v34
	v_exp_f32_e32 v35, v35
	v_exp_f32_e32 v36, v36
	v_exp_f32_e32 v37, v37
	s_waitcnt lgkmcnt(4)
	v_mfma_f32_32x32x16_bf16 v[66:81], v[138:141], v[98:101], v[122:137]
	ds_read_b128 v[138:141], v220 offset:40032
	v_add_f32_e32 v231, v231, v34
	v_add_f32_e32 v232, v232, v35
	v_exp_f32_e32 v38, v38
	v_exp_f32_e32 v39, v39
	v_mfma_f32_32x32x16_bf16 v[82:97], v[142:145], v[98:101], v[122:137]
	ds_read_b128 v[142:145], v220 offset:46688
	v_add_f32_e32 v231, v231, v36
	v_add_f32_e32 v232, v232, v37
	v_exp_f32_e32 v40, v40
	v_exp_f32_e32 v41, v41
	s_waitcnt lgkmcnt(4)
	v_mfma_f32_32x32x16_bf16 v[66:81], v[146:149], v[102:105], v[66:81]
	ds_read_b128 v[146:149], v220 offset:40064
	global_load_dwordx4 v[200:203], v226, s[4:5]
	global_load_dwordx4 v[204:207], v227, s[4:5]
	global_load_dwordx4 v[208:211], v228, s[4:5]
	s_add_u32 s4, s4, 0x6000
	s_addc_u32 s5, s5, 0
	global_load_dwordx4 v[212:215], v229, s[10:11]
	s_add_u32 s10, s10, 0x80
	s_addc_u32 s11, s11, 0
	v_add_f32_e32 v231, v231, v38
	v_add_f32_e32 v232, v232, v39
	v_add_f32_e32 v231, v231, v40
	v_add_f32_e32 v232, v232, v41
	v_cvt_pk_bf16_f32 v34, v34, v35
	v_cvt_pk_bf16_f32 v35, v36, v37
	v_mfma_f32_32x32x16_bf16 v[82:97], v[150:153], v[102:105], v[82:97]
	ds_read_b128 v[150:153], v220 offset:46720
	v_cvt_pk_bf16_f32 v36, v38, v39
	v_cvt_pk_bf16_f32 v37, v40, v41
	v_exp_f32_e32 v42, v42
	v_exp_f32_e32 v43, v43
	s_waitcnt lgkmcnt(4)
	v_mfma_f32_32x32x16_bf16 v[66:81], v[154:157], v[106:109], v[66:81]
	ds_read_b128 v[154:157], v220 offset:40096
	v_exp_f32_e32 v44, v44
	v_exp_f32_e32 v45, v45
	v_add_f32_e32 v231, v231, v42
	v_add_f32_e32 v232, v232, v43
	v_mfma_f32_32x32x16_bf16 v[82:97], v[158:161], v[106:109], v[82:97]
	ds_read_b128 v[158:161], v220 offset:46752
	v_exp_f32_e32 v46, v46
	v_exp_f32_e32 v47, v47
	v_add_f32_e32 v231, v231, v44
	v_add_f32_e32 v232, v232, v45
	v_exp_f32_e32 v48, v48
	s_waitcnt lgkmcnt(4)
	v_mfma_f32_32x32x16_bf16 v[66:81], v[138:141], v[110:113], v[66:81]
	ds_read_b128 v[162:165], v221 offset:18432
	v_exp_f32_e32 v49, v49
	v_add_f32_e32 v231, v231, v46
	v_add_f32_e32 v232, v232, v47
	v_add_f32_e32 v231, v231, v48
	v_mfma_f32_32x32x16_bf16 v[82:97], v[142:145], v[110:113], v[82:97]
	ds_read_b128 v[166:169], v221 offset:23040
	v_add_f32_e32 v232, v232, v49
	v_cvt_pk_bf16_f32 v42, v42, v43
	v_cvt_pk_bf16_f32 v43, v44, v45
	v_cvt_pk_bf16_f32 v44, v46, v47
	v_cvt_pk_bf16_f32 v45, v48, v49
	v_exp_f32_e32 v50, v50
	s_waitcnt lgkmcnt(4)
	v_mfma_f32_32x32x16_bf16 v[66:81], v[146:149], v[114:117], v[66:81]
	ds_read_b128 v[170:173], v221 offset:18464
	v_exp_f32_e32 v51, v51
	v_exp_f32_e32 v52, v52
	v_exp_f32_e32 v53, v53
	v_mfma_f32_32x32x16_bf16 v[82:97], v[150:153], v[114:117], v[82:97]
	ds_read_b128 v[174:177], v221 offset:23072
	v_add_f32_e32 v231, v231, v50
	v_add_f32_e32 v232, v232, v51
	v_exp_f32_e32 v54, v54
	v_exp_f32_e32 v55, v55
	s_waitcnt lgkmcnt(4)
	v_mfma_f32_32x32x16_bf16 v[66:81], v[154:157], v[118:121], v[66:81]
	ds_read_b128 v[180:183], v221 offset:18496
	v_add_f32_e32 v231, v231, v52
	v_add_f32_e32 v232, v232, v53
	v_exp_f32_e32 v56, v56
	v_exp_f32_e32 v57, v57
	v_mfma_f32_32x32x16_bf16 v[82:97], v[158:161], v[118:121], v[82:97]
	ds_read_b128 v[184:187], v221 offset:23104
	v_add_f32_e32 v231, v231, v54
	v_add_f32_e32 v232, v232, v55
	v_add_f32_e32 v231, v231, v56
	v_add_f32_e32 v232, v232, v57
	v_cvt_pk_bf16_f32 v50, v50, v51
	v_cvt_pk_bf16_f32 v51, v52, v53
	v_cvt_pk_bf16_f32 v52, v54, v55
	s_waitcnt lgkmcnt(4)
	v_mfma_f32_32x32x16_bf16 v[2:17], v[162:165], v[34:37], v[2:17]
	ds_read_b128 v[188:191], v221 offset:18528
	v_cvt_pk_bf16_f32 v53, v56, v57
	v_exp_f32_e32 v58, v58
	v_exp_f32_e32 v59, v59
	v_exp_f32_e32 v60, v60
	v_mfma_f32_32x32x16_bf16 v[18:33], v[166:169], v[34:37], v[18:33]
	ds_read_b128 v[192:195], v221 offset:23136
	v_exp_f32_e32 v61, v61
	v_add_f32_e32 v231, v231, v58
	v_add_f32_e32 v232, v232, v59
	v_exp_f32_e32 v62, v62
	s_waitcnt lgkmcnt(4)
	v_mfma_f32_32x32x16_bf16 v[2:17], v[170:173], v[42:45], v[2:17]
	v_exp_f32_e32 v63, v63
	v_add_f32_e32 v231, v231, v60
	v_add_f32_e32 v232, v232, v61
	v_exp_f32_e32 v64, v64
	v_mfma_f32_32x32x16_bf16 v[18:33], v[174:177], v[42:45], v[18:33]
	s_waitcnt vmcnt(4)
	ds_write_b64 v225, v[216:217] offset:0
	ds_write_b64 v225, v[218:219] offset:16
	v_exp_f32_e32 v65, v65
	v_add_f32_e32 v231, v231, v62
	v_add_f32_e32 v232, v232, v63
	v_add_f32_e32 v231, v231, v64
	v_add_f32_e32 v232, v232, v65
	s_waitcnt lgkmcnt(4)
	v_mfma_f32_32x32x16_bf16 v[2:17], v[180:183], v[50:53], v[2:17]
	v_cvt_pk_bf16_f32 v58, v58, v59
	v_cvt_pk_bf16_f32 v59, v60, v61
	v_cvt_pk_bf16_f32 v60, v62, v63
	v_cvt_pk_bf16_f32 v61, v64, v65
	v_max3_f32 v234, v66, v67, v68
	v_max3_f32 v235, v82, v83, v84
	v_mfma_f32_32x32x16_bf16 v[18:33], v[184:187], v[50:53], v[18:33]
	v_max3_f32 v234, v234, v69, v70
	v_max3_f32 v235, v235, v85, v86
	v_max3_f32 v234, v234, v71, v72
	v_max3_f32 v235, v235, v87, v88
	v_max3_f32 v234, v234, v73, v74
	v_max3_f32 v235, v235, v89, v90
	v_max3_f32 v234, v234, v75, v76
	s_waitcnt lgkmcnt(2)
	v_mfma_f32_32x32x16_bf16 v[2:17], v[188:191], v[58:61], v[2:17]
	v_max3_f32 v235, v235, v91, v92
	v_max3_f32 v234, v234, v77, v78
	v_max3_f32 v235, v235, v93, v94
	v_max3_f32 v234, v234, v79, v80
	v_max3_f32 v235, v235, v95, v96
	v_max3_f32 v234, v234, v81, v97
	v_mfma_f32_32x32x16_bf16 v[18:33], v[192:195], v[58:61], v[18:33]
	v_max_f32_e32 v234, v234, v235
	v_mov_b32_e32 v235, v234
	s_nop 1
	v_permlane32_swap_b32_e32 v234, v235
	v_max_f32_e32 v233, v234, v235
	v_cmp_lt_f32_e32 vcc, 4.0, v233
	s_cbranch_vccz .Lmls_nr_p2
	s_nop 15
	v_max_f32_e32 v234, 0, v233
	v_exp_f32_e64 v235, -v234
	v_add_f32_e32 v230, v230, v234
	v_sub_f32_e32 v66, v66, v234
	v_sub_f32_e32 v67, v67, v234
	v_sub_f32_e32 v68, v68, v234
	v_sub_f32_e32 v69, v69, v234
	v_sub_f32_e32 v70, v70, v234
	v_sub_f32_e32 v71, v71, v234
	v_sub_f32_e32 v72, v72, v234
	v_sub_f32_e32 v73, v73, v234
	v_sub_f32_e32 v74, v74, v234
	v_sub_f32_e32 v75, v75, v234
	v_sub_f32_e32 v76, v76, v234
	v_sub_f32_e32 v77, v77, v234
	v_sub_f32_e32 v78, v78, v234
	v_sub_f32_e32 v79, v79, v234
	v_sub_f32_e32 v80, v80, v234
	v_sub_f32_e32 v81, v81, v234
	v_sub_f32_e32 v82, v82, v234
	v_sub_f32_e32 v83, v83, v234
	v_sub_f32_e32 v84, v84, v234
	v_sub_f32_e32 v85, v85, v234
	v_sub_f32_e32 v86, v86, v234
	v_sub_f32_e32 v87, v87, v234
	v_sub_f32_e32 v88, v88, v234
	v_sub_f32_e32 v89, v89, v234
	v_sub_f32_e32 v90, v90, v234
	v_sub_f32_e32 v91, v91, v234
	v_sub_f32_e32 v92, v92, v234
	v_sub_f32_e32 v93, v93, v234
	v_sub_f32_e32 v94, v94, v234
	v_sub_f32_e32 v95, v95, v234
	v_sub_f32_e32 v96, v96, v234
	v_sub_f32_e32 v97, v97, v234
	v_mul_f32_e32 v231, v231, v235
	v_mul_f32_e32 v232, v232, v235
	v_mul_f32_e32 v2, v2, v235
	v_mul_f32_e32 v3, v3, v235
	v_mul_f32_e32 v4, v4, v235
	v_mul_f32_e32 v5, v5, v235
	v_mul_f32_e32 v6, v6, v235
	v_mul_f32_e32 v7, v7, v235
	v_mul_f32_e32 v8, v8, v235
	v_mul_f32_e32 v9, v9, v235
	v_mul_f32_e32 v10, v10, v235
	v_mul_f32_e32 v11, v11, v235
	v_mul_f32_e32 v12, v12, v235
	v_mul_f32_e32 v13, v13, v235
	v_mul_f32_e32 v14, v14, v235
	v_mul_f32_e32 v15, v15, v235
	v_mul_f32_e32 v16, v16, v235
	v_mul_f32_e32 v17, v17, v235
	v_mul_f32_e32 v18, v18, v235
	v_mul_f32_e32 v19, v19, v235
	v_mul_f32_e32 v20, v20, v235
	v_mul_f32_e32 v21, v21, v235
	v_mul_f32_e32 v22, v22, v235
	v_mul_f32_e32 v23, v23, v235
	v_mul_f32_e32 v24, v24, v235
	v_mul_f32_e32 v25, v25, v235
	v_mul_f32_e32 v26, v26, v235
	v_mul_f32_e32 v27, v27, v235
	v_mul_f32_e32 v28, v28, v235
	v_mul_f32_e32 v29, v29, v235
	v_mul_f32_e32 v30, v30, v235
	v_mul_f32_e32 v31, v31, v235
	v_mul_f32_e32 v32, v32, v235
	v_mul_f32_e32 v33, v33, v235
	v_sub_f32_e32 v122, 0, v230
	v_mov_b32_e32 v123, v122
	v_mov_b32_e32 v124, v122
	v_mov_b32_e32 v125, v122
	v_mov_b32_e32 v126, v122
	v_mov_b32_e32 v127, v122
	v_mov_b32_e32 v128, v122
	v_mov_b32_e32 v129, v122
	v_mov_b32_e32 v130, v122
	v_mov_b32_e32 v131, v122
	v_mov_b32_e32 v132, v122
	v_mov_b32_e32 v133, v122
	v_mov_b32_e32 v134, v122
	v_mov_b32_e32 v135, v122
	v_mov_b32_e32 v136, v122
	v_mov_b32_e32 v137, v122
.Lmls_nr_p2:
	ds_read_b128 v[138:141], v220 offset:0
	ds_read_b128 v[142:145], v220 offset:6656
	ds_read_b128 v[146:149], v220 offset:32
	ds_read_b128 v[150:153], v220 offset:6688
	ds_read_b128 v[154:157], v220 offset:64
	ds_read_b128 v[158:161], v220 offset:6720
	s_waitcnt lgkmcnt(6)
	v_exp_f32_e32 v66, v66
	v_exp_f32_e32 v67, v67
	v_exp_f32_e32 v68, v68
	v_exp_f32_e32 v69, v69
	s_waitcnt lgkmcnt(4)
	v_mfma_f32_32x32x16_bf16 v[34:49], v[138:141], v[98:101], v[122:137]
	ds_read_b128 v[138:141], v220 offset:96
	v_add_f32_e32 v231, v231, v66
	v_add_f32_e32 v232, v232, v67
	v_exp_f32_e32 v70, v70
	v_exp_f32_e32 v71, v71
	v_mfma_f32_32x32x16_bf16 v[50:65], v[142:145], v[98:101], v[122:137]
	ds_read_b128 v[142:145], v220 offset:6752
	v_add_f32_e32 v231, v231, v68
	v_add_f32_e32 v232, v232, v69
	v_exp_f32_e32 v72, v72
	v_exp_f32_e32 v73, v73
	s_waitcnt lgkmcnt(4)
	v_mfma_f32_32x32x16_bf16 v[34:49], v[146:149], v[102:105], v[34:49]
	ds_read_b128 v[146:149], v220 offset:128
	global_load_dwordx4 v[216:219], v229, s[10:11]
	s_add_u32 s10, s10, 0x80
	s_addc_u32 s11, s11, 0
	v_add_f32_e32 v231, v231, v70
	v_add_f32_e32 v232, v232, v71
	v_add_f32_e32 v231, v231, v72
	v_add_f32_e32 v232, v232, v73
	v_cvt_pk_bf16_f32 v66, v66, v67
	v_cvt_pk_bf16_f32 v67, v68, v69
	v_mfma_f32_32x32x16_bf16 v[50:65], v[150:153], v[102:105], v[50:65]
	ds_read_b128 v[150:153], v220 offset:6784
	v_cvt_pk_bf16_f32 v68, v70, v71
	v_cvt_pk_bf16_f32 v69, v72, v73
	v_exp_f32_e32 v74, v74
	v_exp_f32_e32 v75, v75
	s_waitcnt lgkmcnt(4)
	v_mfma_f32_32x32x16_bf16 v[34:49], v[154:157], v[106:109], v[34:49]
	ds_read_b128 v[154:157], v220 offset:160
	v_exp_f32_e32 v76, v76
	v_exp_f32_e32 v77, v77
	v_add_f32_e32 v231, v231, v74
	v_add_f32_e32 v232, v232, v75
	v_mfma_f32_32x32x16_bf16 v[50:65], v[158:161], v[106:109], v[50:65]
	ds_read_b128 v[158:161], v220 offset:6816
	v_exp_f32_e32 v78, v78
	v_exp_f32_e32 v79, v79
	v_add_f32_e32 v231, v231, v76
	v_add_f32_e32 v232, v232, v77
	v_exp_f32_e32 v80, v80
	s_waitcnt lgkmcnt(4)
	v_mfma_f32_32x32x16_bf16 v[34:49], v[138:141], v[110:113], v[34:49]
	ds_read_b128 v[162:165], v221 offset:27648
	v_exp_f32_e32 v81, v81
	v_add_f32_e32 v231, v231, v78
	v_add_f32_e32 v232, v232, v79
	v_add_f32_e32 v231, v231, v80
	v_mfma_f32_32x32x16_bf16 v[50:65], v[142:145], v[110:113], v[50:65]
	ds_read_b128 v[166:169], v221 offset:32256
	v_add_f32_e32 v232, v232, v81
	v_cvt_pk_bf16_f32 v74, v74, v75
	v_cvt_pk_bf16_f32 v75, v76, v77
	v_cvt_pk_bf16_f32 v76, v78, v79
	v_cvt_pk_bf16_f32 v77, v80, v81
	v_exp_f32_e32 v82, v82
	s_waitcnt lgkmcnt(4)
	v_mfma_f32_32x32x16_bf16 v[34:49], v[146:149], v[114:117], v[34:49]
	ds_read_b128 v[170:173], v221 offset:27680
	v_exp_f32_e32 v83, v83
	v_exp_f32_e32 v84, v84
	v_exp_f32_e32 v85, v85
	v_mfma_f32_32x32x16_bf16 v[50:65], v[150:153], v[114:117], v[50:65]
	ds_read_b128 v[174:177], v221 offset:32288
	v_add_f32_e32 v231, v231, v82
	v_add_f32_e32 v232, v232, v83
	v_exp_f32_e32 v86, v86
	v_exp_f32_e32 v87, v87
	s_waitcnt lgkmcnt(4)
	v_mfma_f32_32x32x16_bf16 v[34:49], v[154:157], v[118:121], v[34:49]
	ds_read_b128 v[180:183], v221 offset:27712
	v_add_f32_e32 v231, v231, v84
	v_add_f32_e32 v232, v232, v85
	v_exp_f32_e32 v88, v88
	v_exp_f32_e32 v89, v89
	v_mfma_f32_32x32x16_bf16 v[50:65], v[158:161], v[118:121], v[50:65]
	ds_read_b128 v[184:187], v221 offset:32320
	v_add_f32_e32 v231, v231, v86
	v_add_f32_e32 v232, v232, v87
	v_add_f32_e32 v231, v231, v88
	v_add_f32_e32 v232, v232, v89
	v_cvt_pk_bf16_f32 v82, v82, v83
	v_cvt_pk_bf16_f32 v83, v84, v85
	v_cvt_pk_bf16_f32 v84, v86, v87
	s_waitcnt lgkmcnt(4)
	v_mfma_f32_32x32x16_bf16 v[2:17], v[162:165], v[66:69], v[2:17]
	ds_read_b128 v[188:191], v221 offset:27744
	v_cvt_pk_bf16_f32 v85, v88, v89
	v_exp_f32_e32 v90, v90
	v_exp_f32_e32 v91, v91
	v_exp_f32_e32 v92, v92
	v_mfma_f32_32x32x16_bf16 v[18:33], v[166:169], v[66:69], v[18:33]
	ds_read_b128 v[192:195], v221 offset:32352
	v_exp_f32_e32 v93, v93
	v_add_f32_e32 v231, v231, v90
	v_add_f32_e32 v232, v232, v91
	v_exp_f32_e32 v94, v94
	s_waitcnt lgkmcnt(4)
	v_mfma_f32_32x32x16_bf16 v[2:17], v[170:173], v[74:77], v[2:17]
	v_exp_f32_e32 v95, v95
	v_add_f32_e32 v231, v231, v92
	v_add_f32_e32 v232, v232, v93
	v_exp_f32_e32 v96, v96
	v_mfma_f32_32x32x16_bf16 v[18:33], v[174:177], v[74:77], v[18:33]
	s_waitcnt vmcnt(1)
	ds_write_b128 v222, v[200:203] offset:13312
	ds_write_b128 v223, v[204:207] offset:13312
	ds_write_b128 v224, v[208:211] offset:13312
	ds_write_b64 v225, v[212:213] offset:9216
	ds_write_b64 v225, v[214:215] offset:9232
	v_exp_f32_e32 v97, v97
	v_add_f32_e32 v231, v231, v94
	v_add_f32_e32 v232, v232, v95
	v_add_f32_e32 v231, v231, v96
	v_add_f32_e32 v232, v232, v97
	s_waitcnt lgkmcnt(7)
	v_mfma_f32_32x32x16_bf16 v[2:17], v[180:183], v[82:85], v[2:17]
	v_cvt_pk_bf16_f32 v90, v90, v91
	v_cvt_pk_bf16_f32 v91, v92, v93
	v_cvt_pk_bf16_f32 v92, v94, v95
	v_cvt_pk_bf16_f32 v93, v96, v97
	v_max3_f32 v234, v34, v35, v36
	v_max3_f32 v235, v50, v51, v52
	v_mfma_f32_32x32x16_bf16 v[18:33], v[184:187], v[82:85], v[18:33]
	v_max3_f32 v234, v234, v37, v38
	v_max3_f32 v235, v235, v53, v54
	v_max3_f32 v234, v234, v39, v40
	v_max3_f32 v235, v235, v55, v56
	v_max3_f32 v234, v234, v41, v42
	v_max3_f32 v235, v235, v57, v58
	v_max3_f32 v234, v234, v43, v44
	s_waitcnt lgkmcnt(5)
	v_mfma_f32_32x32x16_bf16 v[2:17], v[188:191], v[90:93], v[2:17]
	v_max3_f32 v235, v235, v59, v60
	v_max3_f32 v234, v234, v45, v46
	v_max3_f32 v235, v235, v61, v62
	v_max3_f32 v234, v234, v47, v48
	v_max3_f32 v235, v235, v63, v64
	v_max3_f32 v234, v234, v49, v65
	v_mfma_f32_32x32x16_bf16 v[18:33], v[192:195], v[90:93], v[18:33]
	v_max_f32_e32 v234, v234, v235
	v_mov_b32_e32 v235, v234
	s_nop 1
	v_permlane32_swap_b32_e32 v234, v235
	v_max_f32_e32 v233, v234, v235
	v_cmp_lt_f32_e32 vcc, 4.0, v233
	s_cbranch_vccz .Lmls_nr_p3
	s_nop 15
	v_max_f32_e32 v234, 0, v233
	v_exp_f32_e64 v235, -v234
	v_add_f32_e32 v230, v230, v234
	v_sub_f32_e32 v34, v34, v234
	v_sub_f32_e32 v35, v35, v234
	v_sub_f32_e32 v36, v36, v234
	v_sub_f32_e32 v37, v37, v234
	v_sub_f32_e32 v38, v38, v234
	v_sub_f32_e32 v39, v39, v234
	v_sub_f32_e32 v40, v40, v234
	v_sub_f32_e32 v41, v41, v234
	v_sub_f32_e32 v42, v42, v234
	v_sub_f32_e32 v43, v43, v234
	v_sub_f32_e32 v44, v44, v234
	v_sub_f32_e32 v45, v45, v234
	v_sub_f32_e32 v46, v46, v234
	v_sub_f32_e32 v47, v47, v234
	v_sub_f32_e32 v48, v48, v234
	v_sub_f32_e32 v49, v49, v234
	v_sub_f32_e32 v50, v50, v234
	v_sub_f32_e32 v51, v51, v234
	v_sub_f32_e32 v52, v52, v234
	v_sub_f32_e32 v53, v53, v234
	v_sub_f32_e32 v54, v54, v234
	v_sub_f32_e32 v55, v55, v234
	v_sub_f32_e32 v56, v56, v234
	v_sub_f32_e32 v57, v57, v234
	v_sub_f32_e32 v58, v58, v234
	v_sub_f32_e32 v59, v59, v234
	v_sub_f32_e32 v60, v60, v234
	v_sub_f32_e32 v61, v61, v234
	v_sub_f32_e32 v62, v62, v234
	v_sub_f32_e32 v63, v63, v234
	v_sub_f32_e32 v64, v64, v234
	v_sub_f32_e32 v65, v65, v234
	v_mul_f32_e32 v231, v231, v235
	v_mul_f32_e32 v232, v232, v235
	v_mul_f32_e32 v2, v2, v235
	v_mul_f32_e32 v3, v3, v235
	v_mul_f32_e32 v4, v4, v235
	v_mul_f32_e32 v5, v5, v235
	v_mul_f32_e32 v6, v6, v235
	v_mul_f32_e32 v7, v7, v235
	v_mul_f32_e32 v8, v8, v235
	v_mul_f32_e32 v9, v9, v235
	v_mul_f32_e32 v10, v10, v235
	v_mul_f32_e32 v11, v11, v235
	v_mul_f32_e32 v12, v12, v235
	v_mul_f32_e32 v13, v13, v235
	v_mul_f32_e32 v14, v14, v235
	v_mul_f32_e32 v15, v15, v235
	v_mul_f32_e32 v16, v16, v235
	v_mul_f32_e32 v17, v17, v235
	v_mul_f32_e32 v18, v18, v235
	v_mul_f32_e32 v19, v19, v235
	v_mul_f32_e32 v20, v20, v235
	v_mul_f32_e32 v21, v21, v235
	v_mul_f32_e32 v22, v22, v235
	v_mul_f32_e32 v23, v23, v235
	v_mul_f32_e32 v24, v24, v235
	v_mul_f32_e32 v25, v25, v235
	v_mul_f32_e32 v26, v26, v235
	v_mul_f32_e32 v27, v27, v235
	v_mul_f32_e32 v28, v28, v235
	v_mul_f32_e32 v29, v29, v235
	v_mul_f32_e32 v30, v30, v235
	v_mul_f32_e32 v31, v31, v235
	v_mul_f32_e32 v32, v32, v235
	v_mul_f32_e32 v33, v33, v235
	v_sub_f32_e32 v122, 0, v230
	v_mov_b32_e32 v123, v122
	v_mov_b32_e32 v124, v122
	v_mov_b32_e32 v125, v122
	v_mov_b32_e32 v126, v122
	v_mov_b32_e32 v127, v122
	v_mov_b32_e32 v128, v122
	v_mov_b32_e32 v129, v122
	v_mov_b32_e32 v130, v122
	v_mov_b32_e32 v131, v122
	v_mov_b32_e32 v132, v122
	v_mov_b32_e32 v133, v122
	v_mov_b32_e32 v134, v122
	v_mov_b32_e32 v135, v122
	v_mov_b32_e32 v136, v122
	v_mov_b32_e32 v137, v122
.Lmls_nr_p3:
	s_waitcnt lgkmcnt(0)
	s_barrier
	s_add_i32 s16, s16, -1
	s_cmp_lg_u32 s16, 0
	s_cbranch_scc1 .Lmls_loop
	ds_read_b128 v[138:141], v220 offset:13312
	ds_read_b128 v[142:145], v220 offset:19968
	ds_read_b128 v[146:149], v220 offset:13344
	ds_read_b128 v[150:153], v220 offset:20000
	ds_read_b128 v[154:157], v220 offset:13376
	ds_read_b128 v[158:161], v220 offset:20032
	v_exp_f32_e32 v34, v34
	v_exp_f32_e32 v35, v35
	v_exp_f32_e32 v36, v36
	v_exp_f32_e32 v37, v37
	s_waitcnt lgkmcnt(4)
	v_mfma_f32_32x32x16_bf16 v[66:81], v[138:141], v[98:101], v[122:137]
	ds_read_b128 v[138:141], v220 offset:13408
	v_add_f32_e32 v231, v231, v34
	v_add_f32_e32 v232, v232, v35
	v_exp_f32_e32 v38, v38
	v_exp_f32_e32 v39, v39
	v_mfma_f32_32x32x16_bf16 v[82:97], v[142:145], v[98:101], v[122:137]
	ds_read_b128 v[142:145], v220 offset:20064
	v_add_f32_e32 v231, v231, v36
	v_add_f32_e32 v232, v232, v37
	v_exp_f32_e32 v40, v40
	v_exp_f32_e32 v41, v41
	s_waitcnt lgkmcnt(4)
	v_mfma_f32_32x32x16_bf16 v[66:81], v[146:149], v[102:105], v[66:81]
	ds_read_b128 v[146:149], v220 offset:13440
	global_load_dwordx4 v[200:203], v226, s[4:5]
	global_load_dwordx4 v[204:207], v227, s[4:5]
	global_load_dwordx4 v[208:211], v228, s[4:5]
	s_add_u32 s4, s4, 0x6000
	s_addc_u32 s5, s5, 0
	global_load_dwordx4 v[212:215], v229, s[10:11]
	s_add_u32 s10, s10, 0x80
	s_addc_u32 s11, s11, 0
	v_add_f32_e32 v231, v231, v38
	v_add_f32_e32 v232, v232, v39
	v_add_f32_e32 v231, v231, v40
	v_add_f32_e32 v232, v232, v41
	v_cvt_pk_bf16_f32 v34, v34, v35
	v_cvt_pk_bf16_f32 v35, v36, v37
	v_mfma_f32_32x32x16_bf16 v[82:97], v[150:153], v[102:105], v[82:97]
	ds_read_b128 v[150:153], v220 offset:20096
	v_cvt_pk_bf16_f32 v36, v38, v39
	v_cvt_pk_bf16_f32 v37, v40, v41
	v_exp_f32_e32 v42, v42
	v_exp_f32_e32 v43, v43
	s_waitcnt lgkmcnt(4)
	v_mfma_f32_32x32x16_bf16 v[66:81], v[154:157], v[106:109], v[66:81]
	ds_read_b128 v[154:157], v220 offset:13472
	v_exp_f32_e32 v44, v44
	v_exp_f32_e32 v45, v45
	v_add_f32_e32 v231, v231, v42
	v_add_f32_e32 v232, v232, v43
	v_mfma_f32_32x32x16_bf16 v[82:97], v[158:161], v[106:109], v[82:97]
	ds_read_b128 v[158:161], v220 offset:20128
	v_exp_f32_e32 v46, v46
	v_exp_f32_e32 v47, v47
	v_add_f32_e32 v231, v231, v44
	v_add_f32_e32 v232, v232, v45
	v_exp_f32_e32 v48, v48
	s_waitcnt lgkmcnt(4)
	v_mfma_f32_32x32x16_bf16 v[66:81], v[138:141], v[110:113], v[66:81]
	ds_read_b128 v[162:165], v221 offset:0
	v_exp_f32_e32 v49, v49
	v_add_f32_e32 v231, v231, v46
	v_add_f32_e32 v232, v232, v47
	v_add_f32_e32 v231, v231, v48
	v_mfma_f32_32x32x16_bf16 v[82:97], v[142:145], v[110:113], v[82:97]
	ds_read_b128 v[166:169], v221 offset:4608
	v_add_f32_e32 v232, v232, v49
	v_cvt_pk_bf16_f32 v42, v42, v43
	v_cvt_pk_bf16_f32 v43, v44, v45
	v_cvt_pk_bf16_f32 v44, v46, v47
	v_cvt_pk_bf16_f32 v45, v48, v49
	v_exp_f32_e32 v50, v50
	s_waitcnt lgkmcnt(4)
	v_mfma_f32_32x32x16_bf16 v[66:81], v[146:149], v[114:117], v[66:81]
	ds_read_b128 v[170:173], v221 offset:32
	v_exp_f32_e32 v51, v51
	v_exp_f32_e32 v52, v52
	v_exp_f32_e32 v53, v53
	v_mfma_f32_32x32x16_bf16 v[82:97], v[150:153], v[114:117], v[82:97]
	ds_read_b128 v[174:177], v221 offset:4640
	v_add_f32_e32 v231, v231, v50
	v_add_f32_e32 v232, v232, v51
	v_exp_f32_e32 v54, v54
	v_exp_f32_e32 v55, v55
	s_waitcnt lgkmcnt(4)
	v_mfma_f32_32x32x16_bf16 v[66:81], v[154:157], v[118:121], v[66:81]
	ds_read_b128 v[180:183], v221 offset:64
	v_add_f32_e32 v231, v231, v52
	v_add_f32_e32 v232, v232, v53
	v_exp_f32_e32 v56, v56
	v_exp_f32_e32 v57, v57
	v_mfma_f32_32x32x16_bf16 v[82:97], v[158:161], v[118:121], v[82:97]
	ds_read_b128 v[184:187], v221 offset:4672
	v_add_f32_e32 v231, v231, v54
	v_add_f32_e32 v232, v232, v55
	v_add_f32_e32 v231, v231, v56
	v_add_f32_e32 v232, v232, v57
	v_cvt_pk_bf16_f32 v50, v50, v51
	v_cvt_pk_bf16_f32 v51, v52, v53
	v_cvt_pk_bf16_f32 v52, v54, v55
	s_waitcnt lgkmcnt(4)
	v_mfma_f32_32x32x16_bf16 v[2:17], v[162:165], v[34:37], v[2:17]
	ds_read_b128 v[188:191], v221 offset:96
	v_cvt_pk_bf16_f32 v53, v56, v57
	v_exp_f32_e32 v58, v58
	v_exp_f32_e32 v59, v59
	v_exp_f32_e32 v60, v60
	v_mfma_f32_32x32x16_bf16 v[18:33], v[166:169], v[34:37], v[18:33]
	ds_read_b128 v[192:195], v221 offset:4704
	v_exp_f32_e32 v61, v61
	v_add_f32_e32 v231, v231, v58
	v_add_f32_e32 v232, v232, v59
	v_exp_f32_e32 v62, v62
	s_waitcnt lgkmcnt(4)
	v_mfma_f32_32x32x16_bf16 v[2:17], v[170:173], v[42:45], v[2:17]
	v_exp_f32_e32 v63, v63
	v_add_f32_e32 v231, v231, v60
	v_add_f32_e32 v232, v232, v61
	v_exp_f32_e32 v64, v64
	v_mfma_f32_32x32x16_bf16 v[18:33], v[174:177], v[42:45], v[18:33]
	s_waitcnt vmcnt(4)
	ds_write_b64 v225, v[216:217] offset:18432
	ds_write_b64 v225, v[218:219] offset:18448
	v_exp_f32_e32 v65, v65
	v_add_f32_e32 v231, v231, v62
	v_add_f32_e32 v232, v232, v63
	v_add_f32_e32 v231, v231, v64
	v_add_f32_e32 v232, v232, v65
	s_waitcnt lgkmcnt(4)
	v_mfma_f32_32x32x16_bf16 v[2:17], v[180:183], v[50:53], v[2:17]
	v_cvt_pk_bf16_f32 v58, v58, v59
	v_cvt_pk_bf16_f32 v59, v60, v61
	v_cvt_pk_bf16_f32 v60, v62, v63
	v_cvt_pk_bf16_f32 v61, v64, v65
	v_max3_f32 v234, v66, v67, v68
	v_max3_f32 v235, v82, v83, v84
	v_mfma_f32_32x32x16_bf16 v[18:33], v[184:187], v[50:53], v[18:33]
	v_max3_f32 v234, v234, v69, v70
	v_max3_f32 v235, v235, v85, v86
	v_max3_f32 v234, v234, v71, v72
	v_max3_f32 v235, v235, v87, v88
	v_max3_f32 v234, v234, v73, v74
	v_max3_f32 v235, v235, v89, v90
	v_max3_f32 v234, v234, v75, v76
	s_waitcnt lgkmcnt(2)
	v_mfma_f32_32x32x16_bf16 v[2:17], v[188:191], v[58:61], v[2:17]
	v_max3_f32 v235, v235, v91, v92
	v_max3_f32 v234, v234, v77, v78
	v_max3_f32 v235, v235, v93, v94
	v_max3_f32 v234, v234, v79, v80
	v_max3_f32 v235, v235, v95, v96
	v_max3_f32 v234, v234, v81, v97
	v_mfma_f32_32x32x16_bf16 v[18:33], v[192:195], v[58:61], v[18:33]
	v_max_f32_e32 v234, v234, v235
	v_mov_b32_e32 v235, v234
	s_nop 1
	v_permlane32_swap_b32_e32 v234, v235
	v_max_f32_e32 v233, v234, v235
	v_cmp_lt_f32_e32 vcc, 4.0, v233
	s_cbranch_vccz .Lmls_nr_t0
	s_nop 15
	v_max_f32_e32 v234, 0, v233
	v_exp_f32_e64 v235, -v234
	v_add_f32_e32 v230, v230, v234
	v_sub_f32_e32 v66, v66, v234
	v_sub_f32_e32 v67, v67, v234
	v_sub_f32_e32 v68, v68, v234
	v_sub_f32_e32 v69, v69, v234
	v_sub_f32_e32 v70, v70, v234
	v_sub_f32_e32 v71, v71, v234
	v_sub_f32_e32 v72, v72, v234
	v_sub_f32_e32 v73, v73, v234
	v_sub_f32_e32 v74, v74, v234
	v_sub_f32_e32 v75, v75, v234
	v_sub_f32_e32 v76, v76, v234
	v_sub_f32_e32 v77, v77, v234
	v_sub_f32_e32 v78, v78, v234
	v_sub_f32_e32 v79, v79, v234
	v_sub_f32_e32 v80, v80, v234
	v_sub_f32_e32 v81, v81, v234
	v_sub_f32_e32 v82, v82, v234
	v_sub_f32_e32 v83, v83, v234
	v_sub_f32_e32 v84, v84, v234
	v_sub_f32_e32 v85, v85, v234
	v_sub_f32_e32 v86, v86, v234
	v_sub_f32_e32 v87, v87, v234
	v_sub_f32_e32 v88, v88, v234
	v_sub_f32_e32 v89, v89, v234
	v_sub_f32_e32 v90, v90, v234
	v_sub_f32_e32 v91, v91, v234
	v_sub_f32_e32 v92, v92, v234
	v_sub_f32_e32 v93, v93, v234
	v_sub_f32_e32 v94, v94, v234
	v_sub_f32_e32 v95, v95, v234
	v_sub_f32_e32 v96, v96, v234
	v_sub_f32_e32 v97, v97, v234
	v_mul_f32_e32 v231, v231, v235
	v_mul_f32_e32 v232, v232, v235
	v_mul_f32_e32 v2, v2, v235
	v_mul_f32_e32 v3, v3, v235
	v_mul_f32_e32 v4, v4, v235
	v_mul_f32_e32 v5, v5, v235
	v_mul_f32_e32 v6, v6, v235
	v_mul_f32_e32 v7, v7, v235
	v_mul_f32_e32 v8, v8, v235
	v_mul_f32_e32 v9, v9, v235
	v_mul_f32_e32 v10, v10, v235
	v_mul_f32_e32 v11, v11, v235
	v_mul_f32_e32 v12, v12, v235
	v_mul_f32_e32 v13, v13, v235
	v_mul_f32_e32 v14, v14, v235
	v_mul_f32_e32 v15, v15, v235
	v_mul_f32_e32 v16, v16, v235
	v_mul_f32_e32 v17, v17, v235
	v_mul_f32_e32 v18, v18, v235
	v_mul_f32_e32 v19, v19, v235
	v_mul_f32_e32 v20, v20, v235
	v_mul_f32_e32 v21, v21, v235
	v_mul_f32_e32 v22, v22, v235
	v_mul_f32_e32 v23, v23, v235
	v_mul_f32_e32 v24, v24, v235
	v_mul_f32_e32 v25, v25, v235
	v_mul_f32_e32 v26, v26, v235
	v_mul_f32_e32 v27, v27, v235
	v_mul_f32_e32 v28, v28, v235
	v_mul_f32_e32 v29, v29, v235
	v_mul_f32_e32 v30, v30, v235
	v_mul_f32_e32 v31, v31, v235
	v_mul_f32_e32 v32, v32, v235
	v_mul_f32_e32 v33, v33, v235
	v_sub_f32_e32 v122, 0, v230
	v_mov_b32_e32 v123, v122
	v_mov_b32_e32 v124, v122
	v_mov_b32_e32 v125, v122
	v_mov_b32_e32 v126, v122
	v_mov_b32_e32 v127, v122
	v_mov_b32_e32 v128, v122
	v_mov_b32_e32 v129, v122
	v_mov_b32_e32 v130, v122
	v_mov_b32_e32 v131, v122
	v_mov_b32_e32 v132, v122
	v_mov_b32_e32 v133, v122
	v_mov_b32_e32 v134, v122
	v_mov_b32_e32 v135, v122
	v_mov_b32_e32 v136, v122
	v_mov_b32_e32 v137, v122
.Lmls_nr_t0:
	ds_read_b128 v[138:141], v220 offset:26624
	ds_read_b128 v[142:145], v220 offset:33280
	ds_read_b128 v[146:149], v220 offset:26656
	ds_read_b128 v[150:153], v220 offset:33312
	ds_read_b128 v[154:157], v220 offset:26688
	ds_read_b128 v[158:161], v220 offset:33344
	s_waitcnt lgkmcnt(6)
	v_exp_f32_e32 v66, v66
	v_exp_f32_e32 v67, v67
	v_exp_f32_e32 v68, v68
	v_exp_f32_e32 v69, v69
	s_waitcnt lgkmcnt(4)
	v_mfma_f32_32x32x16_bf16 v[34:49], v[138:141], v[98:101], v[122:137]
	ds_read_b128 v[138:141], v220 offset:26720
	v_add_f32_e32 v231, v231, v66
	v_add_f32_e32 v232, v232, v67
	v_exp_f32_e32 v70, v70
	v_exp_f32_e32 v71, v71
	v_mfma_f32_32x32x16_bf16 v[50:65], v[142:145], v[98:101], v[122:137]
	ds_read_b128 v[142:145], v220 offset:33376
	v_add_f32_e32 v231, v231, v68
	v_add_f32_e32 v232, v232, v69
	v_exp_f32_e32 v72, v72
	v_exp_f32_e32 v73, v73
	s_waitcnt lgkmcnt(4)
	v_mfma_f32_32x32x16_bf16 v[34:49], v[146:149], v[102:105], v[34:49]
	ds_read_b128 v[146:149], v220 offset:26752
	v_add_f32_e32 v231, v231, v70
	v_add_f32_e32 v232, v232, v71
	v_add_f32_e32 v231, v231, v72
	v_add_f32_e32 v232, v232, v73
	v_cvt_pk_bf16_f32 v66, v66, v67
	v_cvt_pk_bf16_f32 v67, v68, v69
	v_mfma_f32_32x32x16_bf16 v[50:65], v[150:153], v[102:105], v[50:65]
	ds_read_b128 v[150:153], v220 offset:33408
	v_cvt_pk_bf16_f32 v68, v70, v71
	v_cvt_pk_bf16_f32 v69, v72, v73
	v_exp_f32_e32 v74, v74
	v_exp_f32_e32 v75, v75
	s_waitcnt lgkmcnt(4)
	v_mfma_f32_32x32x16_bf16 v[34:49], v[154:157], v[106:109], v[34:49]
	ds_read_b128 v[154:157], v220 offset:26784
	v_exp_f32_e32 v76, v76
	v_exp_f32_e32 v77, v77
	v_add_f32_e32 v231, v231, v74
	v_add_f32_e32 v232, v232, v75
	v_mfma_f32_32x32x16_bf16 v[50:65], v[158:161], v[106:109], v[50:65]
	ds_read_b128 v[158:161], v220 offset:33440
	v_exp_f32_e32 v78, v78
	v_exp_f32_e32 v79, v79
	v_add_f32_e32 v231, v231, v76
	v_add_f32_e32 v232, v232, v77
	v_exp_f32_e32 v80, v80
	s_waitcnt lgkmcnt(4)
	v_mfma_f32_32x32x16_bf16 v[34:49], v[138:141], v[110:113], v[34:49]
	ds_read_b128 v[162:165], v221 offset:9216
	v_exp_f32_e32 v81, v81
	v_add_f32_e32 v231, v231, v78
	v_add_f32_e32 v232, v232, v79
	v_add_f32_e32 v231, v231, v80
	v_mfma_f32_32x32x16_bf16 v[50:65], v[142:145], v[110:113], v[50:65]
	ds_read_b128 v[166:169], v221 offset:13824
	v_add_f32_e32 v232, v232, v81
	v_cvt_pk_bf16_f32 v74, v74, v75
	v_cvt_pk_bf16_f32 v75, v76, v77
	v_cvt_pk_bf16_f32 v76, v78, v79
	v_cvt_pk_bf16_f32 v77, v80, v81
	v_exp_f32_e32 v82, v82
	s_waitcnt lgkmcnt(4)
	v_mfma_f32_32x32x16_bf16 v[34:49], v[146:149], v[114:117], v[34:49]
	ds_read_b128 v[170:173], v221 offset:9248
	v_exp_f32_e32 v83, v83
	v_exp_f32_e32 v84, v84
	v_exp_f32_e32 v85, v85
	v_mfma_f32_32x32x16_bf16 v[50:65], v[150:153], v[114:117], v[50:65]
	ds_read_b128 v[174:177], v221 offset:13856
	v_add_f32_e32 v231, v231, v82
	v_add_f32_e32 v232, v232, v83
	v_exp_f32_e32 v86, v86
	v_exp_f32_e32 v87, v87
	s_waitcnt lgkmcnt(4)
	v_mfma_f32_32x32x16_bf16 v[34:49], v[154:157], v[118:121], v[34:49]
	ds_read_b128 v[180:183], v221 offset:9280
	v_add_f32_e32 v231, v231, v84
	v_add_f32_e32 v232, v232, v85
	v_exp_f32_e32 v88, v88
	v_exp_f32_e32 v89, v89
	v_mfma_f32_32x32x16_bf16 v[50:65], v[158:161], v[118:121], v[50:65]
	ds_read_b128 v[184:187], v221 offset:13888
	v_add_f32_e32 v231, v231, v86
	v_add_f32_e32 v232, v232, v87
	v_add_f32_e32 v231, v231, v88
	v_add_f32_e32 v232, v232, v89
	v_cvt_pk_bf16_f32 v82, v82, v83
	v_cvt_pk_bf16_f32 v83, v84, v85
	v_cvt_pk_bf16_f32 v84, v86, v87
	s_waitcnt lgkmcnt(4)
	v_mfma_f32_32x32x16_bf16 v[2:17], v[162:165], v[66:69], v[2:17]
	ds_read_b128 v[188:191], v221 offset:9312
	v_cvt_pk_bf16_f32 v85, v88, v89
	v_exp_f32_e32 v90, v90
	v_exp_f32_e32 v91, v91
	v_exp_f32_e32 v92, v92
	v_mfma_f32_32x32x16_bf16 v[18:33], v[166:169], v[66:69], v[18:33]
	ds_read_b128 v[192:195], v221 offset:13920
	v_exp_f32_e32 v93, v93
	v_add_f32_e32 v231, v231, v90
	v_add_f32_e32 v232, v232, v91
	v_exp_f32_e32 v94, v94
	s_waitcnt lgkmcnt(4)
	v_mfma_f32_32x32x16_bf16 v[2:17], v[170:173], v[74:77], v[2:17]
	v_exp_f32_e32 v95, v95
	v_add_f32_e32 v231, v231, v92
	v_add_f32_e32 v232, v232, v93
	v_exp_f32_e32 v96, v96
	v_mfma_f32_32x32x16_bf16 v[18:33], v[174:177], v[74:77], v[18:33]
	s_waitcnt vmcnt(0)
	ds_write_b128 v238, v[200:203]
	ds_write_b128 v239, v[204:207]
	ds_write_b128 v240, v[208:211]
	ds_write_b64 v225, v[212:213] offset:27648
	ds_write_b64 v225, v[214:215] offset:27664
	v_exp_f32_e32 v97, v97
	v_add_f32_e32 v231, v231, v94
	v_add_f32_e32 v232, v232, v95
	v_add_f32_e32 v231, v231, v96
	v_add_f32_e32 v232, v232, v97
	s_waitcnt lgkmcnt(7)
	v_mfma_f32_32x32x16_bf16 v[2:17], v[180:183], v[82:85], v[2:17]
	v_cvt_pk_bf16_f32 v90, v90, v91
	v_cvt_pk_bf16_f32 v91, v92, v93
	v_cvt_pk_bf16_f32 v92, v94, v95
	v_cvt_pk_bf16_f32 v93, v96, v97
	v_max3_f32 v234, v34, v35, v36
	v_max3_f32 v235, v50, v51, v52
	v_mfma_f32_32x32x16_bf16 v[18:33], v[184:187], v[82:85], v[18:33]
	v_max3_f32 v234, v234, v37, v38
	v_max3_f32 v235, v235, v53, v54
	v_max3_f32 v234, v234, v39, v40
	v_max3_f32 v235, v235, v55, v56
	v_max3_f32 v234, v234, v41, v42
	v_max3_f32 v235, v235, v57, v58
	v_max3_f32 v234, v234, v43, v44
	s_waitcnt lgkmcnt(5)
	v_mfma_f32_32x32x16_bf16 v[2:17], v[188:191], v[90:93], v[2:17]
	v_max3_f32 v235, v235, v59, v60
	v_max3_f32 v234, v234, v45, v46
	v_max3_f32 v235, v235, v61, v62
	v_max3_f32 v234, v234, v47, v48
	v_max3_f32 v235, v235, v63, v64
	v_max3_f32 v234, v234, v49, v65
	v_mfma_f32_32x32x16_bf16 v[18:33], v[192:195], v[90:93], v[18:33]
	v_max_f32_e32 v234, v234, v235
	v_mov_b32_e32 v235, v234
	s_nop 1
	v_permlane32_swap_b32_e32 v234, v235
	v_max_f32_e32 v233, v234, v235
	v_cmp_lt_f32_e32 vcc, 4.0, v233
	s_cbranch_vccz .Lmls_nr_t1
	s_nop 15
	v_max_f32_e32 v234, 0, v233
	v_exp_f32_e64 v235, -v234
	v_add_f32_e32 v230, v230, v234
	v_sub_f32_e32 v34, v34, v234
	v_sub_f32_e32 v35, v35, v234
	v_sub_f32_e32 v36, v36, v234
	v_sub_f32_e32 v37, v37, v234
	v_sub_f32_e32 v38, v38, v234
	v_sub_f32_e32 v39, v39, v234
	v_sub_f32_e32 v40, v40, v234
	v_sub_f32_e32 v41, v41, v234
	v_sub_f32_e32 v42, v42, v234
	v_sub_f32_e32 v43, v43, v234
	v_sub_f32_e32 v44, v44, v234
	v_sub_f32_e32 v45, v45, v234
	v_sub_f32_e32 v46, v46, v234
	v_sub_f32_e32 v47, v47, v234
	v_sub_f32_e32 v48, v48, v234
	v_sub_f32_e32 v49, v49, v234
	v_sub_f32_e32 v50, v50, v234
	v_sub_f32_e32 v51, v51, v234
	v_sub_f32_e32 v52, v52, v234
	v_sub_f32_e32 v53, v53, v234
	v_sub_f32_e32 v54, v54, v234
	v_sub_f32_e32 v55, v55, v234
	v_sub_f32_e32 v56, v56, v234
	v_sub_f32_e32 v57, v57, v234
	v_sub_f32_e32 v58, v58, v234
	v_sub_f32_e32 v59, v59, v234
	v_sub_f32_e32 v60, v60, v234
	v_sub_f32_e32 v61, v61, v234
	v_sub_f32_e32 v62, v62, v234
	v_sub_f32_e32 v63, v63, v234
	v_sub_f32_e32 v64, v64, v234
	v_sub_f32_e32 v65, v65, v234
	v_mul_f32_e32 v231, v231, v235
	v_mul_f32_e32 v232, v232, v235
	v_mul_f32_e32 v2, v2, v235
	v_mul_f32_e32 v3, v3, v235
	v_mul_f32_e32 v4, v4, v235
	v_mul_f32_e32 v5, v5, v235
	v_mul_f32_e32 v6, v6, v235
	v_mul_f32_e32 v7, v7, v235
	v_mul_f32_e32 v8, v8, v235
	v_mul_f32_e32 v9, v9, v235
	v_mul_f32_e32 v10, v10, v235
	v_mul_f32_e32 v11, v11, v235
	v_mul_f32_e32 v12, v12, v235
	v_mul_f32_e32 v13, v13, v235
	v_mul_f32_e32 v14, v14, v235
	v_mul_f32_e32 v15, v15, v235
	v_mul_f32_e32 v16, v16, v235
	v_mul_f32_e32 v17, v17, v235
	v_mul_f32_e32 v18, v18, v235
	v_mul_f32_e32 v19, v19, v235
	v_mul_f32_e32 v20, v20, v235
	v_mul_f32_e32 v21, v21, v235
	v_mul_f32_e32 v22, v22, v235
	v_mul_f32_e32 v23, v23, v235
	v_mul_f32_e32 v24, v24, v235
	v_mul_f32_e32 v25, v25, v235
	v_mul_f32_e32 v26, v26, v235
	v_mul_f32_e32 v27, v27, v235
	v_mul_f32_e32 v28, v28, v235
	v_mul_f32_e32 v29, v29, v235
	v_mul_f32_e32 v30, v30, v235
	v_mul_f32_e32 v31, v31, v235
	v_mul_f32_e32 v32, v32, v235
	v_mul_f32_e32 v33, v33, v235
	v_sub_f32_e32 v122, 0, v230
	v_mov_b32_e32 v123, v122
	v_mov_b32_e32 v124, v122
	v_mov_b32_e32 v125, v122
	v_mov_b32_e32 v126, v122
	v_mov_b32_e32 v127, v122
	v_mov_b32_e32 v128, v122
	v_mov_b32_e32 v129, v122
	v_mov_b32_e32 v130, v122
	v_mov_b32_e32 v131, v122
	v_mov_b32_e32 v132, v122
	v_mov_b32_e32 v133, v122
	v_mov_b32_e32 v134, v122
	v_mov_b32_e32 v135, v122
	v_mov_b32_e32 v136, v122
	v_mov_b32_e32 v137, v122
.Lmls_nr_t1:
	s_waitcnt lgkmcnt(0)
	s_barrier
	global_load_dwordx2 v[200:201], v236, s[14:15] offset:0
	global_load_dwordx2 v[202:203], v236, s[14:15] offset:16
	global_load_dwordx2 v[204:205], v236, s[14:15] offset:32
	global_load_dwordx2 v[206:207], v236, s[14:15] offset:48
	global_load_dwordx2 v[208:209], v236, s[14:15] offset:64
	global_load_dwordx2 v[210:211], v236, s[14:15] offset:80
	global_load_dwordx2 v[212:213], v236, s[14:15] offset:96
	global_load_dwordx2 v[214:215], v236, s[14:15] offset:112
	ds_read_b128 v[138:141], v220 offset:39936
	ds_read_b128 v[142:145], v220 offset:46592
	ds_read_b128 v[146:149], v220 offset:39968
	ds_read_b128 v[150:153], v220 offset:46624
	ds_read_b128 v[154:157], v220 offset:40000
	ds_read_b128 v[158:161], v220 offset:46656
	v_exp_f32_e32 v34, v34
	v_exp_f32_e32 v35, v35
	v_exp_f32_e32 v36, v36
	v_exp_f32_e32 v37, v37
	s_waitcnt lgkmcnt(4)
	v_mfma_f32_32x32x16_bf16 v[66:81], v[138:141], v[98:101], v[122:137]
	ds_read_b128 v[138:141], v220 offset:40032
	v_add_f32_e32 v231, v231, v34
	v_add_f32_e32 v232, v232, v35
	v_exp_f32_e32 v38, v38
	v_exp_f32_e32 v39, v39
	v_mfma_f32_32x32x16_bf16 v[82:97], v[142:145], v[98:101], v[122:137]
	ds_read_b128 v[142:145], v220 offset:46688
	v_add_f32_e32 v231, v231, v36
	v_add_f32_e32 v232, v232, v37
	v_exp_f32_e32 v40, v40
	v_exp_f32_e32 v41, v41
	s_waitcnt lgkmcnt(4)
	v_mfma_f32_32x32x16_bf16 v[66:81], v[146:149], v[102:105], v[66:81]
	ds_read_b128 v[146:149], v220 offset:40064
	v_add_f32_e32 v231, v231, v38
	v_add_f32_e32 v232, v232, v39
	v_add_f32_e32 v231, v231, v40
	v_add_f32_e32 v232, v232, v41
	v_cvt_pk_bf16_f32 v34, v34, v35
	v_cvt_pk_bf16_f32 v35, v36, v37
	v_mfma_f32_32x32x16_bf16 v[82:97], v[150:153], v[102:105], v[82:97]
	ds_read_b128 v[150:153], v220 offset:46720
	v_cvt_pk_bf16_f32 v36, v38, v39
	v_cvt_pk_bf16_f32 v37, v40, v41
	v_exp_f32_e32 v42, v42
	v_exp_f32_e32 v43, v43
	s_waitcnt lgkmcnt(4)
	v_mfma_f32_32x32x16_bf16 v[66:81], v[154:157], v[106:109], v[66:81]
	ds_read_b128 v[154:157], v220 offset:40096
	v_exp_f32_e32 v44, v44
	v_exp_f32_e32 v45, v45
	v_add_f32_e32 v231, v231, v42
	v_add_f32_e32 v232, v232, v43
	v_mfma_f32_32x32x16_bf16 v[82:97], v[158:161], v[106:109], v[82:97]
	ds_read_b128 v[158:161], v220 offset:46752
	v_exp_f32_e32 v46, v46
	v_exp_f32_e32 v47, v47
	v_add_f32_e32 v231, v231, v44
	v_add_f32_e32 v232, v232, v45
	v_exp_f32_e32 v48, v48
	s_waitcnt lgkmcnt(4)
	v_mfma_f32_32x32x16_bf16 v[66:81], v[138:141], v[110:113], v[66:81]
	ds_read_b128 v[162:165], v221 offset:18432
	v_exp_f32_e32 v49, v49
	v_add_f32_e32 v231, v231, v46
	v_add_f32_e32 v232, v232, v47
	v_add_f32_e32 v231, v231, v48
	v_mfma_f32_32x32x16_bf16 v[82:97], v[142:145], v[110:113], v[82:97]
	ds_read_b128 v[166:169], v221 offset:23040
	v_add_f32_e32 v232, v232, v49
	v_cvt_pk_bf16_f32 v42, v42, v43
	v_cvt_pk_bf16_f32 v43, v44, v45
	v_cvt_pk_bf16_f32 v44, v46, v47
	v_cvt_pk_bf16_f32 v45, v48, v49
	v_exp_f32_e32 v50, v50
	s_waitcnt lgkmcnt(4)
	v_mfma_f32_32x32x16_bf16 v[66:81], v[146:149], v[114:117], v[66:81]
	ds_read_b128 v[170:173], v221 offset:18464
	v_exp_f32_e32 v51, v51
	v_exp_f32_e32 v52, v52
	v_exp_f32_e32 v53, v53
	v_mfma_f32_32x32x16_bf16 v[82:97], v[150:153], v[114:117], v[82:97]
	ds_read_b128 v[174:177], v221 offset:23072
	v_add_f32_e32 v231, v231, v50
	v_add_f32_e32 v232, v232, v51
	v_exp_f32_e32 v54, v54
	v_exp_f32_e32 v55, v55
	s_waitcnt lgkmcnt(4)
	v_mfma_f32_32x32x16_bf16 v[66:81], v[154:157], v[118:121], v[66:81]
	ds_read_b128 v[180:183], v221 offset:18496
	v_add_f32_e32 v231, v231, v52
	v_add_f32_e32 v232, v232, v53
	v_exp_f32_e32 v56, v56
	v_exp_f32_e32 v57, v57
	v_mfma_f32_32x32x16_bf16 v[82:97], v[158:161], v[118:121], v[82:97]
	ds_read_b128 v[184:187], v221 offset:23104
	v_add_f32_e32 v231, v231, v54
	v_add_f32_e32 v232, v232, v55
	v_add_f32_e32 v231, v231, v56
	v_add_f32_e32 v232, v232, v57
	v_cvt_pk_bf16_f32 v50, v50, v51
	v_cvt_pk_bf16_f32 v51, v52, v53
	v_cvt_pk_bf16_f32 v52, v54, v55
	s_waitcnt lgkmcnt(4)
	v_mfma_f32_32x32x16_bf16 v[2:17], v[162:165], v[34:37], v[2:17]
	ds_read_b128 v[188:191], v221 offset:18528
	v_cvt_pk_bf16_f32 v53, v56, v57
	v_exp_f32_e32 v58, v58
	v_exp_f32_e32 v59, v59
	v_exp_f32_e32 v60, v60
	v_mfma_f32_32x32x16_bf16 v[18:33], v[166:169], v[34:37], v[18:33]
	ds_read_b128 v[192:195], v221 offset:23136
	v_exp_f32_e32 v61, v61
	v_add_f32_e32 v231, v231, v58
	v_add_f32_e32 v232, v232, v59
	v_exp_f32_e32 v62, v62
	s_waitcnt lgkmcnt(4)
	v_mfma_f32_32x32x16_bf16 v[2:17], v[170:173], v[42:45], v[2:17]
	v_exp_f32_e32 v63, v63
	v_add_f32_e32 v231, v231, v60
	v_add_f32_e32 v232, v232, v61
	v_exp_f32_e32 v64, v64
	v_mfma_f32_32x32x16_bf16 v[18:33], v[174:177], v[42:45], v[18:33]
	v_exp_f32_e32 v65, v65
	v_add_f32_e32 v231, v231, v62
	v_add_f32_e32 v232, v232, v63
	v_add_f32_e32 v231, v231, v64
	v_add_f32_e32 v232, v232, v65
	s_waitcnt lgkmcnt(2)
	v_mfma_f32_32x32x16_bf16 v[2:17], v[180:183], v[50:53], v[2:17]
	v_cvt_pk_bf16_f32 v58, v58, v59
	v_cvt_pk_bf16_f32 v59, v60, v61
	v_cvt_pk_bf16_f32 v60, v62, v63
	v_cvt_pk_bf16_f32 v61, v64, v65
	v_max3_f32 v234, v66, v67, v68
	v_max3_f32 v235, v82, v83, v84
	v_mfma_f32_32x32x16_bf16 v[18:33], v[184:187], v[50:53], v[18:33]
	v_max3_f32 v234, v234, v69, v70
	v_max3_f32 v235, v235, v85, v86
	v_max3_f32 v234, v234, v71, v72
	v_max3_f32 v235, v235, v87, v88
	v_max3_f32 v234, v234, v73, v74
	v_max3_f32 v235, v235, v89, v90
	v_max3_f32 v234, v234, v75, v76
	s_waitcnt lgkmcnt(0)
	v_mfma_f32_32x32x16_bf16 v[2:17], v[188:191], v[58:61], v[2:17]
	v_max3_f32 v235, v235, v91, v92
	v_max3_f32 v234, v234, v77, v78
	v_max3_f32 v235, v235, v93, v94
	v_max3_f32 v234, v234, v79, v80
	v_max3_f32 v235, v235, v95, v96
	v_max3_f32 v234, v234, v81, v97
	v_mfma_f32_32x32x16_bf16 v[18:33], v[192:195], v[58:61], v[18:33]
	v_max_f32_e32 v234, v234, v235
	v_mov_b32_e32 v235, v234
	s_nop 1
	v_permlane32_swap_b32_e32 v234, v235
	v_max_f32_e32 v233, v234, v235
	v_cmp_lt_f32_e32 vcc, 4.0, v233
	s_cbranch_vccz .Lmls_nr_t2
	s_nop 15
	v_max_f32_e32 v234, 0, v233
	v_exp_f32_e64 v235, -v234
	v_add_f32_e32 v230, v230, v234
	v_sub_f32_e32 v66, v66, v234
	v_sub_f32_e32 v67, v67, v234
	v_sub_f32_e32 v68, v68, v234
	v_sub_f32_e32 v69, v69, v234
	v_sub_f32_e32 v70, v70, v234
	v_sub_f32_e32 v71, v71, v234
	v_sub_f32_e32 v72, v72, v234
	v_sub_f32_e32 v73, v73, v234
	v_sub_f32_e32 v74, v74, v234
	v_sub_f32_e32 v75, v75, v234
	v_sub_f32_e32 v76, v76, v234
	v_sub_f32_e32 v77, v77, v234
	v_sub_f32_e32 v78, v78, v234
	v_sub_f32_e32 v79, v79, v234
	v_sub_f32_e32 v80, v80, v234
	v_sub_f32_e32 v81, v81, v234
	v_sub_f32_e32 v82, v82, v234
	v_sub_f32_e32 v83, v83, v234
	v_sub_f32_e32 v84, v84, v234
	v_sub_f32_e32 v85, v85, v234
	v_sub_f32_e32 v86, v86, v234
	v_sub_f32_e32 v87, v87, v234
	v_sub_f32_e32 v88, v88, v234
	v_sub_f32_e32 v89, v89, v234
	v_sub_f32_e32 v90, v90, v234
	v_sub_f32_e32 v91, v91, v234
	v_sub_f32_e32 v92, v92, v234
	v_sub_f32_e32 v93, v93, v234
	v_sub_f32_e32 v94, v94, v234
	v_sub_f32_e32 v95, v95, v234
	v_sub_f32_e32 v96, v96, v234
	v_sub_f32_e32 v97, v97, v234
	v_mul_f32_e32 v231, v231, v235
	v_mul_f32_e32 v232, v232, v235
	v_mul_f32_e32 v2, v2, v235
	v_mul_f32_e32 v3, v3, v235
	v_mul_f32_e32 v4, v4, v235
	v_mul_f32_e32 v5, v5, v235
	v_mul_f32_e32 v6, v6, v235
	v_mul_f32_e32 v7, v7, v235
	v_mul_f32_e32 v8, v8, v235
	v_mul_f32_e32 v9, v9, v235
	v_mul_f32_e32 v10, v10, v235
	v_mul_f32_e32 v11, v11, v235
	v_mul_f32_e32 v12, v12, v235
	v_mul_f32_e32 v13, v13, v235
	v_mul_f32_e32 v14, v14, v235
	v_mul_f32_e32 v15, v15, v235
	v_mul_f32_e32 v16, v16, v235
	v_mul_f32_e32 v17, v17, v235
	v_mul_f32_e32 v18, v18, v235
	v_mul_f32_e32 v19, v19, v235
	v_mul_f32_e32 v20, v20, v235
	v_mul_f32_e32 v21, v21, v235
	v_mul_f32_e32 v22, v22, v235
	v_mul_f32_e32 v23, v23, v235
	v_mul_f32_e32 v24, v24, v235
	v_mul_f32_e32 v25, v25, v235
	v_mul_f32_e32 v26, v26, v235
	v_mul_f32_e32 v27, v27, v235
	v_mul_f32_e32 v28, v28, v235
	v_mul_f32_e32 v29, v29, v235
	v_mul_f32_e32 v30, v30, v235
	v_mul_f32_e32 v31, v31, v235
	v_mul_f32_e32 v32, v32, v235
	v_mul_f32_e32 v33, v33, v235
	v_sub_f32_e32 v122, 0, v230
	v_mov_b32_e32 v123, v122
	v_mov_b32_e32 v124, v122
	v_mov_b32_e32 v125, v122
	v_mov_b32_e32 v126, v122
	v_mov_b32_e32 v127, v122
	v_mov_b32_e32 v128, v122
	v_mov_b32_e32 v129, v122
	v_mov_b32_e32 v130, v122
	v_mov_b32_e32 v131, v122
	v_mov_b32_e32 v132, v122
	v_mov_b32_e32 v133, v122
	v_mov_b32_e32 v134, v122
	v_mov_b32_e32 v135, v122
	v_mov_b32_e32 v136, v122
	v_mov_b32_e32 v137, v122
.Lmls_nr_t2:
	s_waitcnt lgkmcnt(0)
	ds_read_b128 v[162:165], v221 offset:27648
	ds_read_b128 v[166:169], v221 offset:32256
	ds_read_b128 v[170:173], v221 offset:27680
	v_exp_f32_e32 v66, v66
	v_exp_f32_e32 v67, v67
	v_exp_f32_e32 v68, v68
	v_exp_f32_e32 v69, v69
	v_add_f32_e32 v231, v231, v66
	v_add_f32_e32 v232, v232, v67
	v_exp_f32_e32 v70, v70
	v_exp_f32_e32 v71, v71
	v_add_f32_e32 v231, v231, v68
	v_add_f32_e32 v232, v232, v69
	v_exp_f32_e32 v72, v72
	v_exp_f32_e32 v73, v73
	v_add_f32_e32 v231, v231, v70
	v_add_f32_e32 v232, v232, v71
	v_add_f32_e32 v231, v231, v72
	v_add_f32_e32 v232, v232, v73
	v_cvt_pk_bf16_f32 v66, v66, v67
	v_cvt_pk_bf16_f32 v67, v68, v69
	v_cvt_pk_bf16_f32 v68, v70, v71
	v_cvt_pk_bf16_f32 v69, v72, v73
	s_waitcnt lgkmcnt(1)
	s_nop 0
	v_mfma_f32_32x32x16_bf16 v[2:17], v[162:165], v[66:69], v[2:17]
	ds_read_b128 v[174:177], v221 offset:32288
	v_mfma_f32_32x32x16_bf16 v[18:33], v[166:169], v[66:69], v[18:33]
	ds_read_b128 v[180:183], v221 offset:27712
	v_exp_f32_e32 v74, v74
	v_exp_f32_e32 v75, v75
	v_exp_f32_e32 v76, v76
	v_exp_f32_e32 v77, v77
	v_add_f32_e32 v231, v231, v74
	v_add_f32_e32 v232, v232, v75
	v_exp_f32_e32 v78, v78
	v_exp_f32_e32 v79, v79
	v_add_f32_e32 v231, v231, v76
	v_add_f32_e32 v232, v232, v77
	v_exp_f32_e32 v80, v80
	v_exp_f32_e32 v81, v81
	v_add_f32_e32 v231, v231, v78
	v_add_f32_e32 v232, v232, v79
	v_add_f32_e32 v231, v231, v80
	v_add_f32_e32 v232, v232, v81
	v_cvt_pk_bf16_f32 v74, v74, v75
	v_cvt_pk_bf16_f32 v75, v76, v77
	v_cvt_pk_bf16_f32 v76, v78, v79
	v_cvt_pk_bf16_f32 v77, v80, v81
	s_waitcnt lgkmcnt(1)
	s_nop 0
	v_mfma_f32_32x32x16_bf16 v[2:17], v[170:173], v[74:77], v[2:17]
	ds_read_b128 v[184:187], v221 offset:32320
	v_mfma_f32_32x32x16_bf16 v[18:33], v[174:177], v[74:77], v[18:33]
	ds_read_b128 v[188:191], v221 offset:27744
	v_exp_f32_e32 v82, v82
	v_exp_f32_e32 v83, v83
	v_exp_f32_e32 v84, v84
	v_exp_f32_e32 v85, v85
	v_add_f32_e32 v231, v231, v82
	v_add_f32_e32 v232, v232, v83
	v_exp_f32_e32 v86, v86
	v_exp_f32_e32 v87, v87
	v_add_f32_e32 v231, v231, v84
	v_add_f32_e32 v232, v232, v85
	v_exp_f32_e32 v88, v88
	v_exp_f32_e32 v89, v89
	v_add_f32_e32 v231, v231, v86
	v_add_f32_e32 v232, v232, v87
	v_add_f32_e32 v231, v231, v88
	v_add_f32_e32 v232, v232, v89
	v_cvt_pk_bf16_f32 v82, v82, v83
	v_cvt_pk_bf16_f32 v83, v84, v85
	v_cvt_pk_bf16_f32 v84, v86, v87
	v_cvt_pk_bf16_f32 v85, v88, v89
	s_waitcnt lgkmcnt(1)
	s_nop 0
	v_mfma_f32_32x32x16_bf16 v[2:17], v[180:183], v[82:85], v[2:17]
	ds_read_b128 v[192:195], v221 offset:32352
	v_mfma_f32_32x32x16_bf16 v[18:33], v[184:187], v[82:85], v[18:33]
	v_exp_f32_e32 v90, v90
	v_exp_f32_e32 v91, v91
	v_exp_f32_e32 v92, v92
	v_exp_f32_e32 v93, v93
	v_add_f32_e32 v231, v231, v90
	v_add_f32_e32 v232, v232, v91
	v_exp_f32_e32 v94, v94
	v_exp_f32_e32 v95, v95
	v_add_f32_e32 v231, v231, v92
	v_add_f32_e32 v232, v232, v93
	v_exp_f32_e32 v96, v96
	v_exp_f32_e32 v97, v97
	v_add_f32_e32 v231, v231, v94
	v_add_f32_e32 v232, v232, v95
	v_add_f32_e32 v231, v231, v96
	v_add_f32_e32 v232, v232, v97
	v_cvt_pk_bf16_f32 v90, v90, v91
	v_cvt_pk_bf16_f32 v91, v92, v93
	v_cvt_pk_bf16_f32 v92, v94, v95
	v_cvt_pk_bf16_f32 v93, v96, v97
	s_waitcnt lgkmcnt(0)
	s_nop 0
	v_mfma_f32_32x32x16_bf16 v[2:17], v[188:191], v[90:93], v[2:17]
	v_mfma_f32_32x32x16_bf16 v[18:33], v[192:195], v[90:93], v[18:33]
	s_waitcnt lgkmcnt(0)
	s_barrier
	v_add_f32_e32 v231, v231, v232
	v_mov_b32_e32 v235, v231
	s_nop 1
	v_permlane32_swap_b32_e32 v231, v235
	v_add_f32_e32 v234, v231, v235
	v_div_scale_f32 v235, s[22:23], v234, v234, 1.0
	v_rcp_f32_e32 v179, v235
	v_div_scale_f32 v196, vcc, 1.0, v234, 1.0
	v_fma_f32 v197, -v235, v179, 1.0
	v_fmac_f32_e32 v179, v197, v179
	v_mul_f32_e32 v197, v196, v179
	v_fma_f32 v199, -v235, v197, v196
	v_fmac_f32_e32 v197, v199, v179
	v_fma_f32 v235, -v235, v197, v196
	v_div_fmas_f32 v235, v235, v179, v197
	v_div_fixup_f32 v234, v235, v234, 1.0
	s_nop 15
	v_mul_f32_e32 v2, v2, v234
	v_mul_f32_e32 v3, v3, v234
	v_mul_f32_e32 v4, v4, v234
	v_mul_f32_e32 v5, v5, v234
	v_mul_f32_e32 v6, v6, v234
	v_mul_f32_e32 v7, v7, v234
	v_mul_f32_e32 v8, v8, v234
	v_mul_f32_e32 v9, v9, v234
	v_mul_f32_e32 v10, v10, v234
	v_mul_f32_e32 v11, v11, v234
	v_mul_f32_e32 v12, v12, v234
	v_mul_f32_e32 v13, v13, v234
	v_mul_f32_e32 v14, v14, v234
	v_mul_f32_e32 v15, v15, v234
	v_mul_f32_e32 v16, v16, v234
	v_mul_f32_e32 v17, v17, v234
	v_mul_f32_e32 v18, v18, v234
	v_mul_f32_e32 v19, v19, v234
	v_mul_f32_e32 v20, v20, v234
	v_mul_f32_e32 v21, v21, v234
	v_mul_f32_e32 v22, v22, v234
	v_mul_f32_e32 v23, v23, v234
	v_mul_f32_e32 v24, v24, v234
	v_mul_f32_e32 v25, v25, v234
	v_mul_f32_e32 v26, v26, v234
	v_mul_f32_e32 v27, v27, v234
	v_mul_f32_e32 v28, v28, v234
	v_mul_f32_e32 v29, v29, v234
	v_mul_f32_e32 v30, v30, v234
	v_mul_f32_e32 v31, v31, v234
	v_mul_f32_e32 v32, v32, v234
	v_mul_f32_e32 v33, v33, v234
	s_waitcnt vmcnt(0)
	v_lshlrev_b32_e32 v179, 16, v200
	v_and_b32_e32 v196, 0xffff0000, v200
	v_lshlrev_b32_e32 v197, 16, v201
	v_and_b32_e32 v199, 0xffff0000, v201
	v_mul_f32_e32 v2, v2, v179
	v_mul_f32_e32 v3, v3, v196
	v_mul_f32_e32 v4, v4, v197
	v_mul_f32_e32 v5, v5, v199
	v_cvt_pk_bf16_f32 v200, v2, v3
	v_cvt_pk_bf16_f32 v201, v4, v5
	global_store_dwordx2 v236, v[200:201], s[14:15] offset:0
	v_lshlrev_b32_e32 v179, 16, v202
	v_and_b32_e32 v196, 0xffff0000, v202
	v_lshlrev_b32_e32 v197, 16, v203
	v_and_b32_e32 v199, 0xffff0000, v203
	v_mul_f32_e32 v6, v6, v179
	v_mul_f32_e32 v7, v7, v196
	v_mul_f32_e32 v8, v8, v197
	v_mul_f32_e32 v9, v9, v199
	v_cvt_pk_bf16_f32 v202, v6, v7
	v_cvt_pk_bf16_f32 v203, v8, v9
	global_store_dwordx2 v236, v[202:203], s[14:15] offset:16
	v_lshlrev_b32_e32 v179, 16, v204
	v_and_b32_e32 v196, 0xffff0000, v204
	v_lshlrev_b32_e32 v197, 16, v205
	v_and_b32_e32 v199, 0xffff0000, v205
	v_mul_f32_e32 v10, v10, v179
	v_mul_f32_e32 v11, v11, v196
	v_mul_f32_e32 v12, v12, v197
	v_mul_f32_e32 v13, v13, v199
	v_cvt_pk_bf16_f32 v204, v10, v11
	v_cvt_pk_bf16_f32 v205, v12, v13
	global_store_dwordx2 v236, v[204:205], s[14:15] offset:32
	v_lshlrev_b32_e32 v179, 16, v206
	v_and_b32_e32 v196, 0xffff0000, v206
	v_lshlrev_b32_e32 v197, 16, v207
	v_and_b32_e32 v199, 0xffff0000, v207
	v_mul_f32_e32 v14, v14, v179
	v_mul_f32_e32 v15, v15, v196
	v_mul_f32_e32 v16, v16, v197
	v_mul_f32_e32 v17, v17, v199
	v_cvt_pk_bf16_f32 v206, v14, v15
	v_cvt_pk_bf16_f32 v207, v16, v17
	global_store_dwordx2 v236, v[206:207], s[14:15] offset:48
	v_lshlrev_b32_e32 v179, 16, v208
	v_and_b32_e32 v196, 0xffff0000, v208
	v_lshlrev_b32_e32 v197, 16, v209
	v_and_b32_e32 v199, 0xffff0000, v209
	v_mul_f32_e32 v18, v18, v179
	v_mul_f32_e32 v19, v19, v196
	v_mul_f32_e32 v20, v20, v197
	v_mul_f32_e32 v21, v21, v199
	v_cvt_pk_bf16_f32 v208, v18, v19
	v_cvt_pk_bf16_f32 v209, v20, v21
	global_store_dwordx2 v236, v[208:209], s[14:15] offset:64
	v_lshlrev_b32_e32 v179, 16, v210
	v_and_b32_e32 v196, 0xffff0000, v210
	v_lshlrev_b32_e32 v197, 16, v211
	v_and_b32_e32 v199, 0xffff0000, v211
	v_mul_f32_e32 v22, v22, v179
	v_mul_f32_e32 v23, v23, v196
	v_mul_f32_e32 v24, v24, v197
	v_mul_f32_e32 v25, v25, v199
	v_cvt_pk_bf16_f32 v210, v22, v23
	v_cvt_pk_bf16_f32 v211, v24, v25
	global_store_dwordx2 v236, v[210:211], s[14:15] offset:80
	v_lshlrev_b32_e32 v179, 16, v212
	v_and_b32_e32 v196, 0xffff0000, v212
	v_lshlrev_b32_e32 v197, 16, v213
	v_and_b32_e32 v199, 0xffff0000, v213
	v_mul_f32_e32 v26, v26, v179
	v_mul_f32_e32 v27, v27, v196
	v_mul_f32_e32 v28, v28, v197
	v_mul_f32_e32 v29, v29, v199
	v_cvt_pk_bf16_f32 v212, v26, v27
	v_cvt_pk_bf16_f32 v213, v28, v29
	global_store_dwordx2 v236, v[212:213], s[14:15] offset:96
	v_lshlrev_b32_e32 v179, 16, v214
	v_and_b32_e32 v196, 0xffff0000, v214
	v_lshlrev_b32_e32 v197, 16, v215
	v_and_b32_e32 v199, 0xffff0000, v215
	v_mul_f32_e32 v30, v30, v179
	v_mul_f32_e32 v31, v31, v196
	v_mul_f32_e32 v32, v32, v197
	v_mul_f32_e32 v33, v33, v199
	v_cvt_pk_bf16_f32 v214, v30, v31
	v_cvt_pk_bf16_f32 v215, v32, v33
	global_store_dwordx2 v236, v[214:215], s[14:15] offset:112
	s_add_i32 s2, s2, s88
	s_cmpk_lt_i32 s2, 0x200
	s_cbranch_scc1 .Lmla_restart
